# GEMM K loop: step barrier moved before the step's last MFMA group; next step's first A-fragment reads and the DMA after next issued under it
# speedup vs baseline: 1.0127x; 1.0061x over previous
.Lg2_ff2_nodma_0:
	global_load_dwordx4 v[184:187], v160, s[58:59] offset:0
	global_load_dwordx4 v[188:191], v160, s[58:59] offset:1024
	global_load_dwordx4 v[192:195], v161, s[58:59] offset:0
	global_load_dwordx4 v[196:199], v161, s[58:59] offset:1024
	v_mov_b32_e32 v0, 0
	v_mov_b32_e32 v1, 0
	v_mov_b32_e32 v2, 0
	v_mov_b32_e32 v3, 0
	v_mov_b32_e32 v4, 0
	v_mov_b32_e32 v5, 0
	v_mov_b32_e32 v6, 0
	v_mov_b32_e32 v7, 0
	v_mov_b32_e32 v8, 0
	v_mov_b32_e32 v9, 0
	v_mov_b32_e32 v10, 0
	v_mov_b32_e32 v11, 0
	v_mov_b32_e32 v12, 0
	v_mov_b32_e32 v13, 0
	v_mov_b32_e32 v14, 0
	v_mov_b32_e32 v15, 0
	v_mov_b32_e32 v16, 0
	v_mov_b32_e32 v17, 0
	v_mov_b32_e32 v18, 0
	v_mov_b32_e32 v19, 0
	v_mov_b32_e32 v20, 0
	v_mov_b32_e32 v21, 0
	v_mov_b32_e32 v22, 0
	v_mov_b32_e32 v23, 0
	v_mov_b32_e32 v24, 0
	v_mov_b32_e32 v25, 0
	v_mov_b32_e32 v26, 0
	v_mov_b32_e32 v27, 0
	v_mov_b32_e32 v28, 0
	v_mov_b32_e32 v29, 0
	v_mov_b32_e32 v30, 0
	v_mov_b32_e32 v31, 0
	v_mov_b32_e32 v32, 0
	v_mov_b32_e32 v33, 0
	v_mov_b32_e32 v34, 0
	v_mov_b32_e32 v35, 0
	v_mov_b32_e32 v36, 0
	v_mov_b32_e32 v37, 0
	v_mov_b32_e32 v38, 0
	v_mov_b32_e32 v39, 0
	v_mov_b32_e32 v40, 0
	v_mov_b32_e32 v41, 0
	v_mov_b32_e32 v42, 0
	v_mov_b32_e32 v43, 0
	v_mov_b32_e32 v44, 0
	v_mov_b32_e32 v45, 0
	v_mov_b32_e32 v46, 0
	v_mov_b32_e32 v47, 0
	v_mov_b32_e32 v48, 0
	v_mov_b32_e32 v49, 0
	v_mov_b32_e32 v50, 0
	v_mov_b32_e32 v51, 0
	v_mov_b32_e32 v52, 0
	v_mov_b32_e32 v53, 0
	v_mov_b32_e32 v54, 0
	v_mov_b32_e32 v55, 0
	v_mov_b32_e32 v56, 0
	v_mov_b32_e32 v57, 0
	v_mov_b32_e32 v58, 0
	v_mov_b32_e32 v59, 0
	v_mov_b32_e32 v60, 0
	v_mov_b32_e32 v61, 0
	v_mov_b32_e32 v62, 0
	v_mov_b32_e32 v63, 0
	v_mov_b32_e32 v64, 0
	v_mov_b32_e32 v65, 0
	v_mov_b32_e32 v66, 0
	v_mov_b32_e32 v67, 0
	v_mov_b32_e32 v68, 0
	v_mov_b32_e32 v69, 0
	v_mov_b32_e32 v70, 0
	v_mov_b32_e32 v71, 0
	v_mov_b32_e32 v72, 0
	v_mov_b32_e32 v73, 0
	v_mov_b32_e32 v74, 0
	v_mov_b32_e32 v75, 0
	v_mov_b32_e32 v76, 0
	v_mov_b32_e32 v77, 0
	v_mov_b32_e32 v78, 0
	v_mov_b32_e32 v79, 0
	v_mov_b32_e32 v80, 0
	v_mov_b32_e32 v81, 0
	v_mov_b32_e32 v82, 0
	v_mov_b32_e32 v83, 0
	v_mov_b32_e32 v84, 0
	v_mov_b32_e32 v85, 0
	v_mov_b32_e32 v86, 0
	v_mov_b32_e32 v87, 0
	v_mov_b32_e32 v88, 0
	v_mov_b32_e32 v89, 0
	v_mov_b32_e32 v90, 0
	v_mov_b32_e32 v91, 0
	v_mov_b32_e32 v92, 0
	v_mov_b32_e32 v93, 0
	v_mov_b32_e32 v94, 0
	v_mov_b32_e32 v95, 0
	v_mov_b32_e32 v96, 0
	v_mov_b32_e32 v97, 0
	v_mov_b32_e32 v98, 0
	v_mov_b32_e32 v99, 0
	v_mov_b32_e32 v100, 0
	v_mov_b32_e32 v101, 0
	v_mov_b32_e32 v102, 0
	v_mov_b32_e32 v103, 0
	v_mov_b32_e32 v104, 0
	v_mov_b32_e32 v105, 0
	v_mov_b32_e32 v106, 0
	v_mov_b32_e32 v107, 0
	v_mov_b32_e32 v108, 0
	v_mov_b32_e32 v109, 0
	v_mov_b32_e32 v110, 0
	v_mov_b32_e32 v111, 0
	v_mov_b32_e32 v112, 0
	v_mov_b32_e32 v113, 0
	v_mov_b32_e32 v114, 0
	v_mov_b32_e32 v115, 0
	v_mov_b32_e32 v116, 0
	v_mov_b32_e32 v117, 0
	v_mov_b32_e32 v118, 0
	v_mov_b32_e32 v119, 0
	v_mov_b32_e32 v120, 0
	v_mov_b32_e32 v121, 0
	v_mov_b32_e32 v122, 0
	v_mov_b32_e32 v123, 0
	v_mov_b32_e32 v124, 0
	v_mov_b32_e32 v125, 0
	v_mov_b32_e32 v126, 0
	v_mov_b32_e32 v127, 0
	v_mov_b32_e32 v128, 0
	v_mov_b32_e32 v129, 0
	v_mov_b32_e32 v130, 0
	v_mov_b32_e32 v131, 0
	v_mov_b32_e32 v132, 0
	v_mov_b32_e32 v133, 0
	v_mov_b32_e32 v134, 0
	v_mov_b32_e32 v135, 0
	s_mov_b32 s63, 0
	s_waitcnt vmcnt(0)
	s_barrier
	s_add_u32 s56, s56, 0x80
	s_addc_u32 s57, s57, 0
	s_add_u32 m0, s62, 0x8800
	s_add_u32 s4, s56, 0x0
	s_addc_u32 s5, s57, 0
	global_load_lds_dwordx4 v162, s[4:5]
	s_add_u32 m0, s62, 0x9800
	s_add_u32 s4, s56, 0x40000
	s_addc_u32 s5, s57, 0
	global_load_lds_dwordx4 v162, s[4:5]
	s_add_u32 m0, s62, 0xa800
	s_add_u32 s4, s56, 0x80000
	s_addc_u32 s5, s57, 0
	global_load_lds_dwordx4 v162, s[4:5]
	s_add_u32 m0, s62, 0xb800
	s_add_u32 s4, s56, 0xc0000
	s_addc_u32 s5, s57, 0
	global_load_lds_dwordx4 v162, s[4:5]
	s_add_u32 m0, s62, 0xc800
	s_add_u32 s4, s56, 0x100000
	s_addc_u32 s5, s57, 0
	global_load_lds_dwordx4 v162, s[4:5]
	s_add_u32 m0, s62, 0xd800
	s_add_u32 s4, s56, 0x140000
	s_addc_u32 s5, s57, 0
	global_load_lds_dwordx4 v162, s[4:5]
	s_add_u32 m0, s62, 0xe800
	s_add_u32 s4, s56, 0x180000
	s_addc_u32 s5, s57, 0
	global_load_lds_dwordx4 v162, s[4:5]
	s_add_u32 m0, s62, 0xf800
	s_add_u32 s4, s56, 0x1c0000
	s_addc_u32 s5, s57, 0
	global_load_lds_dwordx4 v162, s[4:5]
	s_cmp_gt_u32 s70, 1
	s_cbranch_scc1 .Lg2_ff2_nodma_1
	s_add_u32 m0, s62, 0x10800
	s_add_u32 s4, s56, 0x200000
	s_addc_u32 s5, s57, 0
	global_load_lds_dwordx4 v162, s[4:5]
.Lg2_ff2_nodma_1:
	ds_read_b128 v[136:139], v156 offset:0
	ds_read_b128 v[140:143], v156 offset:2048
	ds_read_b128 v[144:147], v156 offset:4096
	ds_read_b128 v[148:151], v156 offset:6144
.Lg2_ff2_loop17:
	s_add_u32 s58, s58, 0x800
	s_addc_u32 s59, s59, 0
	global_load_dwordx4 v[200:203], v160, s[58:59] offset:0
	global_load_dwordx4 v[204:207], v160, s[58:59] offset:1024
	global_load_dwordx4 v[208:211], v161, s[58:59] offset:0
	global_load_dwordx4 v[240:243], v161, s[58:59] offset:1024
	ds_read_b128 v[164:167], v156 offset:8192
	ds_read_b128 v[168:171], v156 offset:10240
	ds_read_b128 v[172:175], v156 offset:12288
	ds_read_b128 v[176:179], v156 offset:14336
	s_waitcnt lgkmcnt(4)
	v_mfma_f32_16x16x32_bf16 v[0:3], v[184:187], v[136:139], v[0:3]
	v_mfma_f32_16x16x32_bf16 v[4:7], v[192:195], v[136:139], v[4:7]
	v_mfma_f32_16x16x32_bf16 v[8:11], v[184:187], v[140:143], v[8:11]
	v_mfma_f32_16x16x32_bf16 v[12:15], v[192:195], v[140:143], v[12:15]
	v_mfma_f32_16x16x32_bf16 v[16:19], v[184:187], v[144:147], v[16:19]
	v_mfma_f32_16x16x32_bf16 v[20:23], v[192:195], v[144:147], v[20:23]
	v_mfma_f32_16x16x32_bf16 v[24:27], v[184:187], v[148:151], v[24:27]
	v_mfma_f32_16x16x32_bf16 v[28:31], v[192:195], v[148:151], v[28:31]
	ds_read_b128 v[136:139], v156 offset:16384
	ds_read_b128 v[140:143], v156 offset:18432
	ds_read_b128 v[144:147], v156 offset:20480
	ds_read_b128 v[148:151], v156 offset:22528
	s_waitcnt lgkmcnt(4)
	v_mfma_f32_16x16x32_bf16 v[32:35], v[184:187], v[164:167], v[32:35]
	v_mfma_f32_16x16x32_bf16 v[36:39], v[192:195], v[164:167], v[36:39]
	v_mfma_f32_16x16x32_bf16 v[40:43], v[184:187], v[168:171], v[40:43]
	v_mfma_f32_16x16x32_bf16 v[44:47], v[192:195], v[168:171], v[44:47]
	v_mfma_f32_16x16x32_bf16 v[48:51], v[184:187], v[172:175], v[48:51]
	v_mfma_f32_16x16x32_bf16 v[52:55], v[192:195], v[172:175], v[52:55]
	v_mfma_f32_16x16x32_bf16 v[56:59], v[184:187], v[176:179], v[56:59]
	v_mfma_f32_16x16x32_bf16 v[60:63], v[192:195], v[176:179], v[60:63]
	ds_read_b128 v[164:167], v156 offset:24576
	ds_read_b128 v[168:171], v156 offset:26624
	ds_read_b128 v[172:175], v156 offset:28672
	ds_read_b128 v[176:179], v156 offset:30720
	ds_read_b128 v[180:183], v156 offset:32768
	s_waitcnt lgkmcnt(5)
	v_mfma_f32_16x16x32_bf16 v[64:67], v[184:187], v[136:139], v[64:67]
	v_mfma_f32_16x16x32_bf16 v[68:71], v[192:195], v[136:139], v[68:71]
	v_mfma_f32_16x16x32_bf16 v[72:75], v[184:187], v[140:143], v[72:75]
	v_mfma_f32_16x16x32_bf16 v[76:79], v[192:195], v[140:143], v[76:79]
	v_mfma_f32_16x16x32_bf16 v[80:83], v[184:187], v[144:147], v[80:83]
	v_mfma_f32_16x16x32_bf16 v[84:87], v[192:195], v[144:147], v[84:87]
	v_mfma_f32_16x16x32_bf16 v[88:91], v[184:187], v[148:151], v[88:91]
	v_mfma_f32_16x16x32_bf16 v[92:95], v[192:195], v[148:151], v[92:95]
	ds_read_b128 v[136:139], v157 offset:0
	ds_read_b128 v[140:143], v157 offset:2048
	ds_read_b128 v[144:147], v157 offset:4096
	ds_read_b128 v[148:151], v157 offset:6144
	s_waitcnt lgkmcnt(4)
	v_mfma_f32_16x16x32_bf16 v[96:99], v[184:187], v[164:167], v[96:99]
	v_mfma_f32_16x16x32_bf16 v[100:103], v[192:195], v[164:167], v[100:103]
	v_mfma_f32_16x16x32_bf16 v[104:107], v[184:187], v[168:171], v[104:107]
	v_mfma_f32_16x16x32_bf16 v[108:111], v[192:195], v[168:171], v[108:111]
	v_mfma_f32_16x16x32_bf16 v[112:115], v[184:187], v[172:175], v[112:115]
	v_mfma_f32_16x16x32_bf16 v[116:119], v[192:195], v[172:175], v[116:119]
	v_mfma_f32_16x16x32_bf16 v[120:123], v[184:187], v[176:179], v[120:123]
	v_mfma_f32_16x16x32_bf16 v[124:127], v[192:195], v[176:179], v[124:127]
	v_mfma_f32_16x16x32_bf16 v[128:131], v[184:187], v[180:183], v[128:131]
	v_mfma_f32_16x16x32_bf16 v[132:135], v[192:195], v[180:183], v[132:135]
	ds_read_b128 v[164:167], v157 offset:8192
	ds_read_b128 v[168:171], v157 offset:10240
	ds_read_b128 v[172:175], v157 offset:12288
	ds_read_b128 v[176:179], v157 offset:14336
	s_waitcnt lgkmcnt(4)
	v_mfma_f32_16x16x32_bf16 v[0:3], v[188:191], v[136:139], v[0:3]
	v_mfma_f32_16x16x32_bf16 v[4:7], v[196:199], v[136:139], v[4:7]
	v_mfma_f32_16x16x32_bf16 v[8:11], v[188:191], v[140:143], v[8:11]
	v_mfma_f32_16x16x32_bf16 v[12:15], v[196:199], v[140:143], v[12:15]
	v_mfma_f32_16x16x32_bf16 v[16:19], v[188:191], v[144:147], v[16:19]
	v_mfma_f32_16x16x32_bf16 v[20:23], v[196:199], v[144:147], v[20:23]
	v_mfma_f32_16x16x32_bf16 v[24:27], v[188:191], v[148:151], v[24:27]
	v_mfma_f32_16x16x32_bf16 v[28:31], v[196:199], v[148:151], v[28:31]
	ds_read_b128 v[136:139], v157 offset:16384
	ds_read_b128 v[140:143], v157 offset:18432
	ds_read_b128 v[144:147], v157 offset:20480
	ds_read_b128 v[148:151], v157 offset:22528
	s_waitcnt lgkmcnt(4)
	v_mfma_f32_16x16x32_bf16 v[32:35], v[188:191], v[164:167], v[32:35]
	v_mfma_f32_16x16x32_bf16 v[36:39], v[196:199], v[164:167], v[36:39]
	v_mfma_f32_16x16x32_bf16 v[40:43], v[188:191], v[168:171], v[40:43]
	v_mfma_f32_16x16x32_bf16 v[44:47], v[196:199], v[168:171], v[44:47]
	v_mfma_f32_16x16x32_bf16 v[48:51], v[188:191], v[172:175], v[48:51]
	v_mfma_f32_16x16x32_bf16 v[52:55], v[196:199], v[172:175], v[52:55]
	v_mfma_f32_16x16x32_bf16 v[56:59], v[188:191], v[176:179], v[56:59]
	v_mfma_f32_16x16x32_bf16 v[60:63], v[196:199], v[176:179], v[60:63]
	ds_read_b128 v[164:167], v157 offset:24576
	ds_read_b128 v[168:171], v157 offset:26624
	ds_read_b128 v[172:175], v157 offset:28672
	ds_read_b128 v[176:179], v157 offset:30720
	ds_read_b128 v[180:183], v157 offset:32768
	s_waitcnt lgkmcnt(5)
	v_mfma_f32_16x16x32_bf16 v[64:67], v[188:191], v[136:139], v[64:67]
	v_mfma_f32_16x16x32_bf16 v[68:71], v[196:199], v[136:139], v[68:71]
	v_mfma_f32_16x16x32_bf16 v[72:75], v[188:191], v[140:143], v[72:75]
	v_mfma_f32_16x16x32_bf16 v[76:79], v[196:199], v[140:143], v[76:79]
	v_mfma_f32_16x16x32_bf16 v[80:83], v[188:191], v[144:147], v[80:83]
	v_mfma_f32_16x16x32_bf16 v[84:87], v[196:199], v[144:147], v[84:87]
	v_mfma_f32_16x16x32_bf16 v[88:91], v[188:191], v[148:151], v[88:91]
	v_mfma_f32_16x16x32_bf16 v[92:95], v[196:199], v[148:151], v[92:95]
	s_waitcnt vmcnt(0) lgkmcnt(0)
	s_barrier
	s_cmp_ge_u32 s63, 62
	s_cbranch_scc1 .Lg2_ff2_nd17_0
	s_add_u32 s56, s56, 0x80
	s_addc_u32 s57, s57, 0
	s_add_u32 m0, s62, 0x0
	s_add_u32 s4, s56, 0x0
	s_addc_u32 s5, s57, 0
	global_load_lds_dwordx4 v162, s[4:5]
	s_add_u32 m0, s62, 0x1000
	s_add_u32 s4, s56, 0x40000
	s_addc_u32 s5, s57, 0
	global_load_lds_dwordx4 v162, s[4:5]
	s_add_u32 m0, s62, 0x2000
	s_add_u32 s4, s56, 0x80000
	s_addc_u32 s5, s57, 0
	global_load_lds_dwordx4 v162, s[4:5]
	s_add_u32 m0, s62, 0x3000
	s_add_u32 s4, s56, 0xc0000
	s_addc_u32 s5, s57, 0
	global_load_lds_dwordx4 v162, s[4:5]
	s_add_u32 m0, s62, 0x4000
	s_add_u32 s4, s56, 0x100000
	s_addc_u32 s5, s57, 0
	global_load_lds_dwordx4 v162, s[4:5]
	s_add_u32 m0, s62, 0x5000
	s_add_u32 s4, s56, 0x140000
	s_addc_u32 s5, s57, 0
	global_load_lds_dwordx4 v162, s[4:5]
	s_add_u32 m0, s62, 0x6000
	s_add_u32 s4, s56, 0x180000
	s_addc_u32 s5, s57, 0
	global_load_lds_dwordx4 v162, s[4:5]
	s_add_u32 m0, s62, 0x7000
	s_add_u32 s4, s56, 0x1c0000
	s_addc_u32 s5, s57, 0
	global_load_lds_dwordx4 v162, s[4:5]
	s_cmp_gt_u32 s70, 1
	s_cbranch_scc1 .Lg2_ff2_nodma_2
	s_add_u32 m0, s62, 0x8000
	s_add_u32 s4, s56, 0x200000
	s_addc_u32 s5, s57, 0
	global_load_lds_dwordx4 v162, s[4:5]
.Lg2_ff2_nodma_2:
.Lg2_ff2_nd17_0:
	ds_read_b128 v[136:139], v158 offset:0
	ds_read_b128 v[140:143], v158 offset:2048
	ds_read_b128 v[144:147], v158 offset:4096
	ds_read_b128 v[148:151], v158 offset:6144
	v_mfma_f32_16x16x32_bf16 v[96:99], v[188:191], v[164:167], v[96:99]
	v_mfma_f32_16x16x32_bf16 v[100:103], v[196:199], v[164:167], v[100:103]
	v_mfma_f32_16x16x32_bf16 v[104:107], v[188:191], v[168:171], v[104:107]
	v_mfma_f32_16x16x32_bf16 v[108:111], v[196:199], v[168:171], v[108:111]
	v_mfma_f32_16x16x32_bf16 v[112:115], v[188:191], v[172:175], v[112:115]
	v_mfma_f32_16x16x32_bf16 v[116:119], v[196:199], v[172:175], v[116:119]
	v_mfma_f32_16x16x32_bf16 v[120:123], v[188:191], v[176:179], v[120:123]
	v_mfma_f32_16x16x32_bf16 v[124:127], v[196:199], v[176:179], v[124:127]
	v_mfma_f32_16x16x32_bf16 v[128:131], v[188:191], v[180:183], v[128:131]
	v_mfma_f32_16x16x32_bf16 v[132:135], v[196:199], v[180:183], v[132:135]
	s_cmp_ge_u32 s63, 62
	s_cbranch_scc1 .Lg2_ff2_nb17_1
	s_add_u32 s58, s58, 0x800
	s_addc_u32 s59, s59, 0
	global_load_dwordx4 v[184:187], v160, s[58:59] offset:0
	global_load_dwordx4 v[188:191], v160, s[58:59] offset:1024
	global_load_dwordx4 v[192:195], v161, s[58:59] offset:0
	global_load_dwordx4 v[196:199], v161, s[58:59] offset:1024
.Lg2_ff2_nb17_1:
	ds_read_b128 v[164:167], v158 offset:8192
	ds_read_b128 v[168:171], v158 offset:10240
	ds_read_b128 v[172:175], v158 offset:12288
	ds_read_b128 v[176:179], v158 offset:14336
	s_waitcnt lgkmcnt(4)
	v_mfma_f32_16x16x32_bf16 v[0:3], v[200:203], v[136:139], v[0:3]
	v_mfma_f32_16x16x32_bf16 v[4:7], v[208:211], v[136:139], v[4:7]
	v_mfma_f32_16x16x32_bf16 v[8:11], v[200:203], v[140:143], v[8:11]
	v_mfma_f32_16x16x32_bf16 v[12:15], v[208:211], v[140:143], v[12:15]
	v_mfma_f32_16x16x32_bf16 v[16:19], v[200:203], v[144:147], v[16:19]
	v_mfma_f32_16x16x32_bf16 v[20:23], v[208:211], v[144:147], v[20:23]
	v_mfma_f32_16x16x32_bf16 v[24:27], v[200:203], v[148:151], v[24:27]
	v_mfma_f32_16x16x32_bf16 v[28:31], v[208:211], v[148:151], v[28:31]
	ds_read_b128 v[136:139], v158 offset:16384
	ds_read_b128 v[140:143], v158 offset:18432
	ds_read_b128 v[144:147], v158 offset:20480
	ds_read_b128 v[148:151], v158 offset:22528
	s_waitcnt lgkmcnt(4)
	v_mfma_f32_16x16x32_bf16 v[32:35], v[200:203], v[164:167], v[32:35]
	v_mfma_f32_16x16x32_bf16 v[36:39], v[208:211], v[164:167], v[36:39]
	v_mfma_f32_16x16x32_bf16 v[40:43], v[200:203], v[168:171], v[40:43]
	v_mfma_f32_16x16x32_bf16 v[44:47], v[208:211], v[168:171], v[44:47]
	v_mfma_f32_16x16x32_bf16 v[48:51], v[200:203], v[172:175], v[48:51]
	v_mfma_f32_16x16x32_bf16 v[52:55], v[208:211], v[172:175], v[52:55]
	v_mfma_f32_16x16x32_bf16 v[56:59], v[200:203], v[176:179], v[56:59]
	v_mfma_f32_16x16x32_bf16 v[60:63], v[208:211], v[176:179], v[60:63]
	ds_read_b128 v[164:167], v158 offset:24576
	ds_read_b128 v[168:171], v158 offset:26624
	ds_read_b128 v[172:175], v158 offset:28672
	ds_read_b128 v[176:179], v158 offset:30720
	ds_read_b128 v[180:183], v158 offset:32768
	s_waitcnt lgkmcnt(5)
	v_mfma_f32_16x16x32_bf16 v[64:67], v[200:203], v[136:139], v[64:67]
	v_mfma_f32_16x16x32_bf16 v[68:71], v[208:211], v[136:139], v[68:71]
	v_mfma_f32_16x16x32_bf16 v[72:75], v[200:203], v[140:143], v[72:75]
	v_mfma_f32_16x16x32_bf16 v[76:79], v[208:211], v[140:143], v[76:79]
	v_mfma_f32_16x16x32_bf16 v[80:83], v[200:203], v[144:147], v[80:83]
	v_mfma_f32_16x16x32_bf16 v[84:87], v[208:211], v[144:147], v[84:87]
	v_mfma_f32_16x16x32_bf16 v[88:91], v[200:203], v[148:151], v[88:91]
	v_mfma_f32_16x16x32_bf16 v[92:95], v[208:211], v[148:151], v[92:95]
	ds_read_b128 v[136:139], v159 offset:0
	ds_read_b128 v[140:143], v159 offset:2048
	ds_read_b128 v[144:147], v159 offset:4096
	ds_read_b128 v[148:151], v159 offset:6144
	s_waitcnt lgkmcnt(4)
	v_mfma_f32_16x16x32_bf16 v[96:99], v[200:203], v[164:167], v[96:99]
	v_mfma_f32_16x16x32_bf16 v[100:103], v[208:211], v[164:167], v[100:103]
	v_mfma_f32_16x16x32_bf16 v[104:107], v[200:203], v[168:171], v[104:107]
	v_mfma_f32_16x16x32_bf16 v[108:111], v[208:211], v[168:171], v[108:111]
	v_mfma_f32_16x16x32_bf16 v[112:115], v[200:203], v[172:175], v[112:115]
	v_mfma_f32_16x16x32_bf16 v[116:119], v[208:211], v[172:175], v[116:119]
	v_mfma_f32_16x16x32_bf16 v[120:123], v[200:203], v[176:179], v[120:123]
	v_mfma_f32_16x16x32_bf16 v[124:127], v[208:211], v[176:179], v[124:127]
	v_mfma_f32_16x16x32_bf16 v[128:131], v[200:203], v[180:183], v[128:131]
	v_mfma_f32_16x16x32_bf16 v[132:135], v[208:211], v[180:183], v[132:135]
	ds_read_b128 v[164:167], v159 offset:8192
	ds_read_b128 v[168:171], v159 offset:10240
	ds_read_b128 v[172:175], v159 offset:12288
	ds_read_b128 v[176:179], v159 offset:14336
	s_waitcnt lgkmcnt(4)
	v_mfma_f32_16x16x32_bf16 v[0:3], v[204:207], v[136:139], v[0:3]
	v_mfma_f32_16x16x32_bf16 v[4:7], v[240:243], v[136:139], v[4:7]
	v_mfma_f32_16x16x32_bf16 v[8:11], v[204:207], v[140:143], v[8:11]
	v_mfma_f32_16x16x32_bf16 v[12:15], v[240:243], v[140:143], v[12:15]
	v_mfma_f32_16x16x32_bf16 v[16:19], v[204:207], v[144:147], v[16:19]
	v_mfma_f32_16x16x32_bf16 v[20:23], v[240:243], v[144:147], v[20:23]
	v_mfma_f32_16x16x32_bf16 v[24:27], v[204:207], v[148:151], v[24:27]
	v_mfma_f32_16x16x32_bf16 v[28:31], v[240:243], v[148:151], v[28:31]
	ds_read_b128 v[136:139], v159 offset:16384
	ds_read_b128 v[140:143], v159 offset:18432
	ds_read_b128 v[144:147], v159 offset:20480
	ds_read_b128 v[148:151], v159 offset:22528
	s_waitcnt lgkmcnt(4)
	v_mfma_f32_16x16x32_bf16 v[32:35], v[204:207], v[164:167], v[32:35]
	v_mfma_f32_16x16x32_bf16 v[36:39], v[240:243], v[164:167], v[36:39]
	v_mfma_f32_16x16x32_bf16 v[40:43], v[204:207], v[168:171], v[40:43]
	v_mfma_f32_16x16x32_bf16 v[44:47], v[240:243], v[168:171], v[44:47]
	v_mfma_f32_16x16x32_bf16 v[48:51], v[204:207], v[172:175], v[48:51]
	v_mfma_f32_16x16x32_bf16 v[52:55], v[240:243], v[172:175], v[52:55]
	v_mfma_f32_16x16x32_bf16 v[56:59], v[204:207], v[176:179], v[56:59]
	v_mfma_f32_16x16x32_bf16 v[60:63], v[240:243], v[176:179], v[60:63]
	ds_read_b128 v[164:167], v159 offset:24576
	ds_read_b128 v[168:171], v159 offset:26624
	ds_read_b128 v[172:175], v159 offset:28672
	ds_read_b128 v[176:179], v159 offset:30720
	ds_read_b128 v[180:183], v159 offset:32768
	s_waitcnt lgkmcnt(5)
	v_mfma_f32_16x16x32_bf16 v[64:67], v[204:207], v[136:139], v[64:67]
	v_mfma_f32_16x16x32_bf16 v[68:71], v[240:243], v[136:139], v[68:71]
	v_mfma_f32_16x16x32_bf16 v[72:75], v[204:207], v[140:143], v[72:75]
	v_mfma_f32_16x16x32_bf16 v[76:79], v[240:243], v[140:143], v[76:79]
	v_mfma_f32_16x16x32_bf16 v[80:83], v[204:207], v[144:147], v[80:83]
	v_mfma_f32_16x16x32_bf16 v[84:87], v[240:243], v[144:147], v[84:87]
	v_mfma_f32_16x16x32_bf16 v[88:91], v[204:207], v[148:151], v[88:91]
	v_mfma_f32_16x16x32_bf16 v[92:95], v[240:243], v[148:151], v[92:95]
	s_waitcnt vmcnt(0) lgkmcnt(0)
	s_barrier
	s_cmp_ge_u32 s63, 62
	s_cbranch_scc1 .Lg2_ff2_nd17_1
	s_add_u32 s56, s56, 0x80
	s_addc_u32 s57, s57, 0
	s_add_u32 m0, s62, 0x8800
	s_add_u32 s4, s56, 0x0
	s_addc_u32 s5, s57, 0
	global_load_lds_dwordx4 v162, s[4:5]
	s_add_u32 m0, s62, 0x9800
	s_add_u32 s4, s56, 0x40000
	s_addc_u32 s5, s57, 0
	global_load_lds_dwordx4 v162, s[4:5]
	s_add_u32 m0, s62, 0xa800
	s_add_u32 s4, s56, 0x80000
	s_addc_u32 s5, s57, 0
	global_load_lds_dwordx4 v162, s[4:5]
	s_add_u32 m0, s62, 0xb800
	s_add_u32 s4, s56, 0xc0000
	s_addc_u32 s5, s57, 0
	global_load_lds_dwordx4 v162, s[4:5]
	s_add_u32 m0, s62, 0xc800
	s_add_u32 s4, s56, 0x100000
	s_addc_u32 s5, s57, 0
	global_load_lds_dwordx4 v162, s[4:5]
	s_add_u32 m0, s62, 0xd800
	s_add_u32 s4, s56, 0x140000
	s_addc_u32 s5, s57, 0
	global_load_lds_dwordx4 v162, s[4:5]
	s_add_u32 m0, s62, 0xe800
	s_add_u32 s4, s56, 0x180000
	s_addc_u32 s5, s57, 0
	global_load_lds_dwordx4 v162, s[4:5]
	s_add_u32 m0, s62, 0xf800
	s_add_u32 s4, s56, 0x1c0000
	s_addc_u32 s5, s57, 0
	global_load_lds_dwordx4 v162, s[4:5]
	s_cmp_gt_u32 s70, 1
	s_cbranch_scc1 .Lg2_ff2_nodma_3
	s_add_u32 m0, s62, 0x10800
	s_add_u32 s4, s56, 0x200000
	s_addc_u32 s5, s57, 0
	global_load_lds_dwordx4 v162, s[4:5]

.Lg2_ff2_nd17_1:
	v_mfma_f32_16x16x32_bf16 v[96:99], v[204:207], v[164:167], v[96:99]
	v_mfma_f32_16x16x32_bf16 v[100:103], v[240:243], v[164:167], v[100:103]
	v_mfma_f32_16x16x32_bf16 v[104:107], v[204:207], v[168:171], v[104:107]
	v_mfma_f32_16x16x32_bf16 v[108:111], v[240:243], v[168:171], v[108:111]
	v_mfma_f32_16x16x32_bf16 v[112:115], v[204:207], v[172:175], v[112:115]
	v_mfma_f32_16x16x32_bf16 v[116:119], v[240:243], v[172:175], v[116:119]
	v_mfma_f32_16x16x32_bf16 v[120:123], v[204:207], v[176:179], v[120:123]
	v_mfma_f32_16x16x32_bf16 v[124:127], v[240:243], v[176:179], v[124:127]
	v_mfma_f32_16x16x32_bf16 v[128:131], v[204:207], v[180:183], v[128:131]
	v_mfma_f32_16x16x32_bf16 v[132:135], v[240:243], v[180:183], v[132:135]
	s_add_i32 s63, s63, 2
	s_cmp_lt_u32 s63, 64
	s_cbranch_scc1 .Lg2_ff2_loop17
	s_branch .Lg2_ff2_episel
.Lg2_ff2_k16:
	s_add_u32 m0, s62, 0x0
	s_add_u32 s4, s56, 0x0
	s_addc_u32 s5, s57, 0
	global_load_lds_dwordx4 v162, s[4:5]
	s_add_u32 m0, s62, 0x1000
	s_add_u32 s4, s56, 0x40000
	s_addc_u32 s5, s57, 0
	global_load_lds_dwordx4 v162, s[4:5]
	s_add_u32 m0, s62, 0x2000
	s_add_u32 s4, s56, 0x80000
	s_addc_u32 s5, s57, 0
	global_load_lds_dwordx4 v162, s[4:5]
	s_add_u32 m0, s62, 0x3000
	s_add_u32 s4, s56, 0xc0000
	s_addc_u32 s5, s57, 0
	global_load_lds_dwordx4 v162, s[4:5]
	s_add_u32 m0, s62, 0x4000
	s_add_u32 s4, s56, 0x100000
	s_addc_u32 s5, s57, 0
	global_load_lds_dwordx4 v162, s[4:5]
	s_add_u32 m0, s62, 0x5000
	s_add_u32 s4, s56, 0x140000
	s_addc_u32 s5, s57, 0
	global_load_lds_dwordx4 v162, s[4:5]
	s_add_u32 m0, s62, 0x6000
	s_add_u32 s4, s56, 0x180000
	s_addc_u32 s5, s57, 0
	global_load_lds_dwordx4 v162, s[4:5]
	s_add_u32 m0, s62, 0x7000
	s_add_u32 s4, s56, 0x1c0000
	s_addc_u32 s5, s57, 0
	global_load_lds_dwordx4 v162, s[4:5]
	global_load_dwordx4 v[184:187], v160, s[58:59] offset:0
	global_load_dwordx4 v[188:191], v160, s[58:59] offset:1024
	global_load_dwordx4 v[192:195], v161, s[58:59] offset:0
	global_load_dwordx4 v[196:199], v161, s[58:59] offset:1024
	v_mov_b32_e32 v0, 0
	v_mov_b32_e32 v1, 0
	v_mov_b32_e32 v2, 0
	v_mov_b32_e32 v3, 0
	v_mov_b32_e32 v4, 0
	v_mov_b32_e32 v5, 0
	v_mov_b32_e32 v6, 0
	v_mov_b32_e32 v7, 0
	v_mov_b32_e32 v8, 0
	v_mov_b32_e32 v9, 0
	v_mov_b32_e32 v10, 0
	v_mov_b32_e32 v11, 0
	v_mov_b32_e32 v12, 0
	v_mov_b32_e32 v13, 0
	v_mov_b32_e32 v14, 0
	v_mov_b32_e32 v15, 0
	v_mov_b32_e32 v16, 0
	v_mov_b32_e32 v17, 0
	v_mov_b32_e32 v18, 0
	v_mov_b32_e32 v19, 0
	v_mov_b32_e32 v20, 0
	v_mov_b32_e32 v21, 0
	v_mov_b32_e32 v22, 0
	v_mov_b32_e32 v23, 0
	v_mov_b32_e32 v24, 0
	v_mov_b32_e32 v25, 0
	v_mov_b32_e32 v26, 0
	v_mov_b32_e32 v27, 0
	v_mov_b32_e32 v28, 0
	v_mov_b32_e32 v29, 0
	v_mov_b32_e32 v30, 0
	v_mov_b32_e32 v31, 0
	v_mov_b32_e32 v32, 0
	v_mov_b32_e32 v33, 0
	v_mov_b32_e32 v34, 0
	v_mov_b32_e32 v35, 0
	v_mov_b32_e32 v36, 0
	v_mov_b32_e32 v37, 0
	v_mov_b32_e32 v38, 0
	v_mov_b32_e32 v39, 0
	v_mov_b32_e32 v40, 0
	v_mov_b32_e32 v41, 0
	v_mov_b32_e32 v42, 0
	v_mov_b32_e32 v43, 0
	v_mov_b32_e32 v44, 0
	v_mov_b32_e32 v45, 0
	v_mov_b32_e32 v46, 0
	v_mov_b32_e32 v47, 0
	v_mov_b32_e32 v48, 0
	v_mov_b32_e32 v49, 0
	v_mov_b32_e32 v50, 0
	v_mov_b32_e32 v51, 0
	v_mov_b32_e32 v52, 0
	v_mov_b32_e32 v53, 0
	v_mov_b32_e32 v54, 0
	v_mov_b32_e32 v55, 0
	v_mov_b32_e32 v56, 0
	v_mov_b32_e32 v57, 0
	v_mov_b32_e32 v58, 0
	v_mov_b32_e32 v59, 0
	v_mov_b32_e32 v60, 0
	v_mov_b32_e32 v61, 0
	v_mov_b32_e32 v62, 0
	v_mov_b32_e32 v63, 0
	v_mov_b32_e32 v64, 0
	v_mov_b32_e32 v65, 0
	v_mov_b32_e32 v66, 0
	v_mov_b32_e32 v67, 0
	v_mov_b32_e32 v68, 0
	v_mov_b32_e32 v69, 0
	v_mov_b32_e32 v70, 0
	v_mov_b32_e32 v71, 0
	v_mov_b32_e32 v72, 0
	v_mov_b32_e32 v73, 0
	v_mov_b32_e32 v74, 0
	v_mov_b32_e32 v75, 0
	v_mov_b32_e32 v76, 0
	v_mov_b32_e32 v77, 0
	v_mov_b32_e32 v78, 0
	v_mov_b32_e32 v79, 0
	v_mov_b32_e32 v80, 0
	v_mov_b32_e32 v81, 0
	v_mov_b32_e32 v82, 0
	v_mov_b32_e32 v83, 0
	v_mov_b32_e32 v84, 0
	v_mov_b32_e32 v85, 0
	v_mov_b32_e32 v86, 0
	v_mov_b32_e32 v87, 0
	v_mov_b32_e32 v88, 0
	v_mov_b32_e32 v89, 0
	v_mov_b32_e32 v90, 0
	v_mov_b32_e32 v91, 0
	v_mov_b32_e32 v92, 0
	v_mov_b32_e32 v93, 0
	v_mov_b32_e32 v94, 0
	v_mov_b32_e32 v95, 0
	v_mov_b32_e32 v96, 0
	v_mov_b32_e32 v97, 0
	v_mov_b32_e32 v98, 0
	v_mov_b32_e32 v99, 0
	v_mov_b32_e32 v100, 0
	v_mov_b32_e32 v101, 0
	v_mov_b32_e32 v102, 0
	v_mov_b32_e32 v103, 0
	v_mov_b32_e32 v104, 0
	v_mov_b32_e32 v105, 0
	v_mov_b32_e32 v106, 0
	v_mov_b32_e32 v107, 0
	v_mov_b32_e32 v108, 0
	v_mov_b32_e32 v109, 0
	v_mov_b32_e32 v110, 0
	v_mov_b32_e32 v111, 0
	v_mov_b32_e32 v112, 0
	v_mov_b32_e32 v113, 0
	v_mov_b32_e32 v114, 0
	v_mov_b32_e32 v115, 0
	v_mov_b32_e32 v116, 0
	v_mov_b32_e32 v117, 0
	v_mov_b32_e32 v118, 0
	v_mov_b32_e32 v119, 0
	v_mov_b32_e32 v120, 0
	v_mov_b32_e32 v121, 0
	v_mov_b32_e32 v122, 0
	v_mov_b32_e32 v123, 0
	v_mov_b32_e32 v124, 0
	v_mov_b32_e32 v125, 0
	v_mov_b32_e32 v126, 0
	v_mov_b32_e32 v127, 0
	s_mov_b32 s63, 0
	s_waitcnt vmcnt(0)
	s_barrier
	s_add_u32 s56, s56, 0x80
	s_addc_u32 s57, s57, 0
	s_add_u32 m0, s62, 0x8800
	s_add_u32 s4, s56, 0x0
	s_addc_u32 s5, s57, 0
	global_load_lds_dwordx4 v162, s[4:5]
	s_add_u32 m0, s62, 0x9800
	s_add_u32 s4, s56, 0x40000
	s_addc_u32 s5, s57, 0
	global_load_lds_dwordx4 v162, s[4:5]
	s_add_u32 m0, s62, 0xa800
	s_add_u32 s4, s56, 0x80000
	s_addc_u32 s5, s57, 0
	global_load_lds_dwordx4 v162, s[4:5]
	s_add_u32 m0, s62, 0xb800
	s_add_u32 s4, s56, 0xc0000
	s_addc_u32 s5, s57, 0
	global_load_lds_dwordx4 v162, s[4:5]
	s_add_u32 m0, s62, 0xc800
	s_add_u32 s4, s56, 0x100000
	s_addc_u32 s5, s57, 0
	global_load_lds_dwordx4 v162, s[4:5]
	s_add_u32 m0, s62, 0xd800
	s_add_u32 s4, s56, 0x140000
	s_addc_u32 s5, s57, 0
	global_load_lds_dwordx4 v162, s[4:5]
	s_add_u32 m0, s62, 0xe800
	s_add_u32 s4, s56, 0x180000
	s_addc_u32 s5, s57, 0
	global_load_lds_dwordx4 v162, s[4:5]
	s_add_u32 m0, s62, 0xf800
	s_add_u32 s4, s56, 0x1c0000
	s_addc_u32 s5, s57, 0
	global_load_lds_dwordx4 v162, s[4:5]
	ds_read_b128 v[136:139], v156 offset:0
	ds_read_b128 v[140:143], v156 offset:2048
	ds_read_b128 v[144:147], v156 offset:4096
	ds_read_b128 v[148:151], v156 offset:6144
.Lg2_ff2_loop16:
	s_add_u32 s58, s58, 0x800
	s_addc_u32 s59, s59, 0
	global_load_dwordx4 v[200:203], v160, s[58:59] offset:0
	global_load_dwordx4 v[204:207], v160, s[58:59] offset:1024
	global_load_dwordx4 v[208:211], v161, s[58:59] offset:0
	global_load_dwordx4 v[240:243], v161, s[58:59] offset:1024
	ds_read_b128 v[164:167], v156 offset:8192
	ds_read_b128 v[168:171], v156 offset:10240
	ds_read_b128 v[172:175], v156 offset:12288
	ds_read_b128 v[176:179], v156 offset:14336
	s_waitcnt lgkmcnt(4)
	v_mfma_f32_16x16x32_bf16 v[0:3], v[184:187], v[136:139], v[0:3]
	v_mfma_f32_16x16x32_bf16 v[4:7], v[192:195], v[136:139], v[4:7]
	v_mfma_f32_16x16x32_bf16 v[8:11], v[184:187], v[140:143], v[8:11]
	v_mfma_f32_16x16x32_bf16 v[12:15], v[192:195], v[140:143], v[12:15]
	v_mfma_f32_16x16x32_bf16 v[16:19], v[184:187], v[144:147], v[16:19]
	v_mfma_f32_16x16x32_bf16 v[20:23], v[192:195], v[144:147], v[20:23]
	v_mfma_f32_16x16x32_bf16 v[24:27], v[184:187], v[148:151], v[24:27]
	v_mfma_f32_16x16x32_bf16 v[28:31], v[192:195], v[148:151], v[28:31]
	ds_read_b128 v[136:139], v156 offset:16384
	ds_read_b128 v[140:143], v156 offset:18432
	ds_read_b128 v[144:147], v156 offset:20480
	ds_read_b128 v[148:151], v156 offset:22528
	s_waitcnt lgkmcnt(4)
	v_mfma_f32_16x16x32_bf16 v[32:35], v[184:187], v[164:167], v[32:35]
	v_mfma_f32_16x16x32_bf16 v[36:39], v[192:195], v[164:167], v[36:39]
	v_mfma_f32_16x16x32_bf16 v[40:43], v[184:187], v[168:171], v[40:43]
	v_mfma_f32_16x16x32_bf16 v[44:47], v[192:195], v[168:171], v[44:47]
	v_mfma_f32_16x16x32_bf16 v[48:51], v[184:187], v[172:175], v[48:51]
	v_mfma_f32_16x16x32_bf16 v[52:55], v[192:195], v[172:175], v[52:55]
	v_mfma_f32_16x16x32_bf16 v[56:59], v[184:187], v[176:179], v[56:59]
	v_mfma_f32_16x16x32_bf16 v[60:63], v[192:195], v[176:179], v[60:63]
	ds_read_b128 v[164:167], v156 offset:24576
	ds_read_b128 v[168:171], v156 offset:26624
	ds_read_b128 v[172:175], v156 offset:28672
	ds_read_b128 v[176:179], v156 offset:30720
	s_waitcnt lgkmcnt(4)
	v_mfma_f32_16x16x32_bf16 v[64:67], v[184:187], v[136:139], v[64:67]
	v_mfma_f32_16x16x32_bf16 v[68:71], v[192:195], v[136:139], v[68:71]
	v_mfma_f32_16x16x32_bf16 v[72:75], v[184:187], v[140:143], v[72:75]
	v_mfma_f32_16x16x32_bf16 v[76:79], v[192:195], v[140:143], v[76:79]
	v_mfma_f32_16x16x32_bf16 v[80:83], v[184:187], v[144:147], v[80:83]
	v_mfma_f32_16x16x32_bf16 v[84:87], v[192:195], v[144:147], v[84:87]
	v_mfma_f32_16x16x32_bf16 v[88:91], v[184:187], v[148:151], v[88:91]
	v_mfma_f32_16x16x32_bf16 v[92:95], v[192:195], v[148:151], v[92:95]
	ds_read_b128 v[136:139], v157 offset:0
	ds_read_b128 v[140:143], v157 offset:2048
	ds_read_b128 v[144:147], v157 offset:4096
	ds_read_b128 v[148:151], v157 offset:6144
	s_waitcnt lgkmcnt(4)
	v_mfma_f32_16x16x32_bf16 v[96:99], v[184:187], v[164:167], v[96:99]
	v_mfma_f32_16x16x32_bf16 v[100:103], v[192:195], v[164:167], v[100:103]
	v_mfma_f32_16x16x32_bf16 v[104:107], v[184:187], v[168:171], v[104:107]
	v_mfma_f32_16x16x32_bf16 v[108:111], v[192:195], v[168:171], v[108:111]
	v_mfma_f32_16x16x32_bf16 v[112:115], v[184:187], v[172:175], v[112:115]
	v_mfma_f32_16x16x32_bf16 v[116:119], v[192:195], v[172:175], v[116:119]
	v_mfma_f32_16x16x32_bf16 v[120:123], v[184:187], v[176:179], v[120:123]
	v_mfma_f32_16x16x32_bf16 v[124:127], v[192:195], v[176:179], v[124:127]
	ds_read_b128 v[164:167], v157 offset:8192
	ds_read_b128 v[168:171], v157 offset:10240
	ds_read_b128 v[172:175], v157 offset:12288
	ds_read_b128 v[176:179], v157 offset:14336
	s_waitcnt lgkmcnt(4)
	v_mfma_f32_16x16x32_bf16 v[0:3], v[188:191], v[136:139], v[0:3]
	v_mfma_f32_16x16x32_bf16 v[4:7], v[196:199], v[136:139], v[4:7]
	v_mfma_f32_16x16x32_bf16 v[8:11], v[188:191], v[140:143], v[8:11]
	v_mfma_f32_16x16x32_bf16 v[12:15], v[196:199], v[140:143], v[12:15]
	v_mfma_f32_16x16x32_bf16 v[16:19], v[188:191], v[144:147], v[16:19]
	v_mfma_f32_16x16x32_bf16 v[20:23], v[196:199], v[144:147], v[20:23]
	v_mfma_f32_16x16x32_bf16 v[24:27], v[188:191], v[148:151], v[24:27]
	v_mfma_f32_16x16x32_bf16 v[28:31], v[196:199], v[148:151], v[28:31]
	ds_read_b128 v[136:139], v157 offset:16384
	ds_read_b128 v[140:143], v157 offset:18432
	ds_read_b128 v[144:147], v157 offset:20480
	ds_read_b128 v[148:151], v157 offset:22528
	s_waitcnt lgkmcnt(4)
	v_mfma_f32_16x16x32_bf16 v[32:35], v[188:191], v[164:167], v[32:35]
	v_mfma_f32_16x16x32_bf16 v[36:39], v[196:199], v[164:167], v[36:39]
	v_mfma_f32_16x16x32_bf16 v[40:43], v[188:191], v[168:171], v[40:43]
	v_mfma_f32_16x16x32_bf16 v[44:47], v[196:199], v[168:171], v[44:47]
	v_mfma_f32_16x16x32_bf16 v[48:51], v[188:191], v[172:175], v[48:51]
	v_mfma_f32_16x16x32_bf16 v[52:55], v[196:199], v[172:175], v[52:55]
	v_mfma_f32_16x16x32_bf16 v[56:59], v[188:191], v[176:179], v[56:59]
	v_mfma_f32_16x16x32_bf16 v[60:63], v[196:199], v[176:179], v[60:63]
	ds_read_b128 v[164:167], v157 offset:24576
	ds_read_b128 v[168:171], v157 offset:26624
	ds_read_b128 v[172:175], v157 offset:28672
	ds_read_b128 v[176:179], v157 offset:30720
	s_waitcnt lgkmcnt(4)
	v_mfma_f32_16x16x32_bf16 v[64:67], v[188:191], v[136:139], v[64:67]
	v_mfma_f32_16x16x32_bf16 v[68:71], v[196:199], v[136:139], v[68:71]
	v_mfma_f32_16x16x32_bf16 v[72:75], v[188:191], v[140:143], v[72:75]
	v_mfma_f32_16x16x32_bf16 v[76:79], v[196:199], v[140:143], v[76:79]
	v_mfma_f32_16x16x32_bf16 v[80:83], v[188:191], v[144:147], v[80:83]
	v_mfma_f32_16x16x32_bf16 v[84:87], v[196:199], v[144:147], v[84:87]
	v_mfma_f32_16x16x32_bf16 v[88:91], v[188:191], v[148:151], v[88:91]
	v_mfma_f32_16x16x32_bf16 v[92:95], v[196:199], v[148:151], v[92:95]
	s_waitcnt vmcnt(0) lgkmcnt(0)
	s_barrier
	s_cmp_ge_u32 s63, 62
	s_cbranch_scc1 .Lg2_ff2_nd16_0
	s_add_u32 s56, s56, 0x80
	s_addc_u32 s57, s57, 0
	s_add_u32 m0, s62, 0x0
	s_add_u32 s4, s56, 0x0
	s_addc_u32 s5, s57, 0
	global_load_lds_dwordx4 v162, s[4:5]
	s_add_u32 m0, s62, 0x1000
	s_add_u32 s4, s56, 0x40000
	s_addc_u32 s5, s57, 0
	global_load_lds_dwordx4 v162, s[4:5]
	s_add_u32 m0, s62, 0x2000
	s_add_u32 s4, s56, 0x80000
	s_addc_u32 s5, s57, 0
	global_load_lds_dwordx4 v162, s[4:5]
	s_add_u32 m0, s62, 0x3000
	s_add_u32 s4, s56, 0xc0000
	s_addc_u32 s5, s57, 0
	global_load_lds_dwordx4 v162, s[4:5]
	s_add_u32 m0, s62, 0x4000
	s_add_u32 s4, s56, 0x100000
	s_addc_u32 s5, s57, 0
	global_load_lds_dwordx4 v162, s[4:5]
	s_add_u32 m0, s62, 0x5000
	s_add_u32 s4, s56, 0x140000
	s_addc_u32 s5, s57, 0
	global_load_lds_dwordx4 v162, s[4:5]
	s_add_u32 m0, s62, 0x6000
	s_add_u32 s4, s56, 0x180000
	s_addc_u32 s5, s57, 0
	global_load_lds_dwordx4 v162, s[4:5]
	s_add_u32 m0, s62, 0x7000
	s_add_u32 s4, s56, 0x1c0000
	s_addc_u32 s5, s57, 0
	global_load_lds_dwordx4 v162, s[4:5]
.Lg2_ff2_nd16_0:
	ds_read_b128 v[136:139], v158 offset:0
	ds_read_b128 v[140:143], v158 offset:2048
	ds_read_b128 v[144:147], v158 offset:4096
	ds_read_b128 v[148:151], v158 offset:6144
	v_mfma_f32_16x16x32_bf16 v[96:99], v[188:191], v[164:167], v[96:99]
	v_mfma_f32_16x16x32_bf16 v[100:103], v[196:199], v[164:167], v[100:103]
	v_mfma_f32_16x16x32_bf16 v[104:107], v[188:191], v[168:171], v[104:107]
	v_mfma_f32_16x16x32_bf16 v[108:111], v[196:199], v[168:171], v[108:111]
	v_mfma_f32_16x16x32_bf16 v[112:115], v[188:191], v[172:175], v[112:115]
	v_mfma_f32_16x16x32_bf16 v[116:119], v[196:199], v[172:175], v[116:119]
	v_mfma_f32_16x16x32_bf16 v[120:123], v[188:191], v[176:179], v[120:123]
	v_mfma_f32_16x16x32_bf16 v[124:127], v[196:199], v[176:179], v[124:127]
	s_cmp_ge_u32 s63, 62
	s_cbranch_scc1 .Lg2_ff2_nb16_1
	s_add_u32 s58, s58, 0x800
	s_addc_u32 s59, s59, 0
	global_load_dwordx4 v[184:187], v160, s[58:59] offset:0
	global_load_dwordx4 v[188:191], v160, s[58:59] offset:1024
	global_load_dwordx4 v[192:195], v161, s[58:59] offset:0
	global_load_dwordx4 v[196:199], v161, s[58:59] offset:1024
.Lg2_ff2_nb16_1:
	ds_read_b128 v[164:167], v158 offset:8192
	ds_read_b128 v[168:171], v158 offset:10240
	ds_read_b128 v[172:175], v158 offset:12288
	ds_read_b128 v[176:179], v158 offset:14336
	s_waitcnt lgkmcnt(4)
	v_mfma_f32_16x16x32_bf16 v[0:3], v[200:203], v[136:139], v[0:3]
	v_mfma_f32_16x16x32_bf16 v[4:7], v[208:211], v[136:139], v[4:7]
	v_mfma_f32_16x16x32_bf16 v[8:11], v[200:203], v[140:143], v[8:11]
	v_mfma_f32_16x16x32_bf16 v[12:15], v[208:211], v[140:143], v[12:15]
	v_mfma_f32_16x16x32_bf16 v[16:19], v[200:203], v[144:147], v[16:19]
	v_mfma_f32_16x16x32_bf16 v[20:23], v[208:211], v[144:147], v[20:23]
	v_mfma_f32_16x16x32_bf16 v[24:27], v[200:203], v[148:151], v[24:27]
	v_mfma_f32_16x16x32_bf16 v[28:31], v[208:211], v[148:151], v[28:31]
	ds_read_b128 v[136:139], v158 offset:16384
	ds_read_b128 v[140:143], v158 offset:18432
	ds_read_b128 v[144:147], v158 offset:20480
	ds_read_b128 v[148:151], v158 offset:22528
	s_waitcnt lgkmcnt(4)
	v_mfma_f32_16x16x32_bf16 v[32:35], v[200:203], v[164:167], v[32:35]
	v_mfma_f32_16x16x32_bf16 v[36:39], v[208:211], v[164:167], v[36:39]
	v_mfma_f32_16x16x32_bf16 v[40:43], v[200:203], v[168:171], v[40:43]
	v_mfma_f32_16x16x32_bf16 v[44:47], v[208:211], v[168:171], v[44:47]
	v_mfma_f32_16x16x32_bf16 v[48:51], v[200:203], v[172:175], v[48:51]
	v_mfma_f32_16x16x32_bf16 v[52:55], v[208:211], v[172:175], v[52:55]
	v_mfma_f32_16x16x32_bf16 v[56:59], v[200:203], v[176:179], v[56:59]
	v_mfma_f32_16x16x32_bf16 v[60:63], v[208:211], v[176:179], v[60:63]
	ds_read_b128 v[164:167], v158 offset:24576
	ds_read_b128 v[168:171], v158 offset:26624
	ds_read_b128 v[172:175], v158 offset:28672
	ds_read_b128 v[176:179], v158 offset:30720
	s_waitcnt lgkmcnt(4)
	v_mfma_f32_16x16x32_bf16 v[64:67], v[200:203], v[136:139], v[64:67]
	v_mfma_f32_16x16x32_bf16 v[68:71], v[208:211], v[136:139], v[68:71]
	v_mfma_f32_16x16x32_bf16 v[72:75], v[200:203], v[140:143], v[72:75]
	v_mfma_f32_16x16x32_bf16 v[76:79], v[208:211], v[140:143], v[76:79]
	v_mfma_f32_16x16x32_bf16 v[80:83], v[200:203], v[144:147], v[80:83]
	v_mfma_f32_16x16x32_bf16 v[84:87], v[208:211], v[144:147], v[84:87]
	v_mfma_f32_16x16x32_bf16 v[88:91], v[200:203], v[148:151], v[88:91]
	v_mfma_f32_16x16x32_bf16 v[92:95], v[208:211], v[148:151], v[92:95]
	ds_read_b128 v[136:139], v159 offset:0
	ds_read_b128 v[140:143], v159 offset:2048
	ds_read_b128 v[144:147], v159 offset:4096
	ds_read_b128 v[148:151], v159 offset:6144
	s_waitcnt lgkmcnt(4)
	v_mfma_f32_16x16x32_bf16 v[96:99], v[200:203], v[164:167], v[96:99]
	v_mfma_f32_16x16x32_bf16 v[100:103], v[208:211], v[164:167], v[100:103]
	v_mfma_f32_16x16x32_bf16 v[104:107], v[200:203], v[168:171], v[104:107]
	v_mfma_f32_16x16x32_bf16 v[108:111], v[208:211], v[168:171], v[108:111]
	v_mfma_f32_16x16x32_bf16 v[112:115], v[200:203], v[172:175], v[112:115]
	v_mfma_f32_16x16x32_bf16 v[116:119], v[208:211], v[172:175], v[116:119]
	v_mfma_f32_16x16x32_bf16 v[120:123], v[200:203], v[176:179], v[120:123]
	v_mfma_f32_16x16x32_bf16 v[124:127], v[208:211], v[176:179], v[124:127]
	ds_read_b128 v[164:167], v159 offset:8192
	ds_read_b128 v[168:171], v159 offset:10240
	ds_read_b128 v[172:175], v159 offset:12288
	ds_read_b128 v[176:179], v159 offset:14336
	s_waitcnt lgkmcnt(4)
	v_mfma_f32_16x16x32_bf16 v[0:3], v[204:207], v[136:139], v[0:3]
	v_mfma_f32_16x16x32_bf16 v[4:7], v[240:243], v[136:139], v[4:7]
	v_mfma_f32_16x16x32_bf16 v[8:11], v[204:207], v[140:143], v[8:11]
	v_mfma_f32_16x16x32_bf16 v[12:15], v[240:243], v[140:143], v[12:15]
	v_mfma_f32_16x16x32_bf16 v[16:19], v[204:207], v[144:147], v[16:19]
	v_mfma_f32_16x16x32_bf16 v[20:23], v[240:243], v[144:147], v[20:23]
	v_mfma_f32_16x16x32_bf16 v[24:27], v[204:207], v[148:151], v[24:27]
	v_mfma_f32_16x16x32_bf16 v[28:31], v[240:243], v[148:151], v[28:31]
	ds_read_b128 v[136:139], v159 offset:16384
	ds_read_b128 v[140:143], v159 offset:18432
	ds_read_b128 v[144:147], v159 offset:20480
	ds_read_b128 v[148:151], v159 offset:22528
	s_waitcnt lgkmcnt(4)
	v_mfma_f32_16x16x32_bf16 v[32:35], v[204:207], v[164:167], v[32:35]
	v_mfma_f32_16x16x32_bf16 v[36:39], v[240:243], v[164:167], v[36:39]
	v_mfma_f32_16x16x32_bf16 v[40:43], v[204:207], v[168:171], v[40:43]
	v_mfma_f32_16x16x32_bf16 v[44:47], v[240:243], v[168:171], v[44:47]
	v_mfma_f32_16x16x32_bf16 v[48:51], v[204:207], v[172:175], v[48:51]
	v_mfma_f32_16x16x32_bf16 v[52:55], v[240:243], v[172:175], v[52:55]
	v_mfma_f32_16x16x32_bf16 v[56:59], v[204:207], v[176:179], v[56:59]
	v_mfma_f32_16x16x32_bf16 v[60:63], v[240:243], v[176:179], v[60:63]
	ds_read_b128 v[164:167], v159 offset:24576
	ds_read_b128 v[168:171], v159 offset:26624
	ds_read_b128 v[172:175], v159 offset:28672
	ds_read_b128 v[176:179], v159 offset:30720
	s_waitcnt lgkmcnt(4)
	v_mfma_f32_16x16x32_bf16 v[64:67], v[204:207], v[136:139], v[64:67]
	v_mfma_f32_16x16x32_bf16 v[68:71], v[240:243], v[136:139], v[68:71]
	v_mfma_f32_16x16x32_bf16 v[72:75], v[204:207], v[140:143], v[72:75]
	v_mfma_f32_16x16x32_bf16 v[76:79], v[240:243], v[140:143], v[76:79]
	v_mfma_f32_16x16x32_bf16 v[80:83], v[204:207], v[144:147], v[80:83]
	v_mfma_f32_16x16x32_bf16 v[84:87], v[240:243], v[144:147], v[84:87]
	v_mfma_f32_16x16x32_bf16 v[88:91], v[204:207], v[148:151], v[88:91]
	v_mfma_f32_16x16x32_bf16 v[92:95], v[240:243], v[148:151], v[92:95]
	s_waitcnt vmcnt(0) lgkmcnt(0)
	s_barrier
	s_cmp_ge_u32 s63, 62
	s_cbranch_scc1 .Lg2_ff2_nd16_1
	s_add_u32 s56, s56, 0x80
	s_addc_u32 s57, s57, 0
	s_add_u32 m0, s62, 0x8800
	s_add_u32 s4, s56, 0x0
	s_addc_u32 s5, s57, 0
	global_load_lds_dwordx4 v162, s[4:5]
	s_add_u32 m0, s62, 0x9800
	s_add_u32 s4, s56, 0x40000
	s_addc_u32 s5, s57, 0
	global_load_lds_dwordx4 v162, s[4:5]
	s_add_u32 m0, s62, 0xa800
	s_add_u32 s4, s56, 0x80000
	s_addc_u32 s5, s57, 0
	global_load_lds_dwordx4 v162, s[4:5]
	s_add_u32 m0, s62, 0xb800
	s_add_u32 s4, s56, 0xc0000
	s_addc_u32 s5, s57, 0
	global_load_lds_dwordx4 v162, s[4:5]
	s_add_u32 m0, s62, 0xc800
	s_add_u32 s4, s56, 0x100000
	s_addc_u32 s5, s57, 0
	global_load_lds_dwordx4 v162, s[4:5]
	s_add_u32 m0, s62, 0xd800
	s_add_u32 s4, s56, 0x140000
	s_addc_u32 s5, s57, 0
	global_load_lds_dwordx4 v162, s[4:5]
	s_add_u32 m0, s62, 0xe800
	s_add_u32 s4, s56, 0x180000
	s_addc_u32 s5, s57, 0
	global_load_lds_dwordx4 v162, s[4:5]
	s_add_u32 m0, s62, 0xf800
	s_add_u32 s4, s56, 0x1c0000
	s_addc_u32 s5, s57, 0
	global_load_lds_dwordx4 v162, s[4:5]
	ds_read_b128 v[136:139], v156 offset:0
	ds_read_b128 v[140:143], v156 offset:2048
	ds_read_b128 v[144:147], v156 offset:4096
	ds_read_b128 v[148:151], v156 offset:6144
.Lg2_ff2_nd16_1:
	v_mfma_f32_16x16x32_bf16 v[96:99], v[204:207], v[164:167], v[96:99]
	v_mfma_f32_16x16x32_bf16 v[100:103], v[240:243], v[164:167], v[100:103]
	v_mfma_f32_16x16x32_bf16 v[104:107], v[204:207], v[168:171], v[104:107]
	v_mfma_f32_16x16x32_bf16 v[108:111], v[240:243], v[168:171], v[108:111]
	v_mfma_f32_16x16x32_bf16 v[112:115], v[204:207], v[172:175], v[112:115]
	v_mfma_f32_16x16x32_bf16 v[116:119], v[240:243], v[172:175], v[116:119]
	v_mfma_f32_16x16x32_bf16 v[120:123], v[204:207], v[176:179], v[120:123]
	v_mfma_f32_16x16x32_bf16 v[124:127], v[240:243], v[176:179], v[124:127]
	s_add_i32 s63, s63, 2
	s_cmp_lt_u32 s63, 64
	s_cbranch_scc1 .Lg2_ff2_loop16
	s_branch .Lg2_ff2_episel

.Lg2_ff1_nodma_0:
	global_load_dwordx4 v[184:187], v160, s[58:59] offset:0
	global_load_dwordx4 v[188:191], v160, s[58:59] offset:1024
	global_load_dwordx4 v[192:195], v161, s[58:59] offset:0
	global_load_dwordx4 v[196:199], v161, s[58:59] offset:1024
	v_mov_b32_e32 v0, 0
	v_mov_b32_e32 v1, 0
	v_mov_b32_e32 v2, 0
	v_mov_b32_e32 v3, 0
	v_mov_b32_e32 v4, 0
	v_mov_b32_e32 v5, 0
	v_mov_b32_e32 v6, 0
	v_mov_b32_e32 v7, 0
	v_mov_b32_e32 v8, 0
	v_mov_b32_e32 v9, 0
	v_mov_b32_e32 v10, 0
	v_mov_b32_e32 v11, 0
	v_mov_b32_e32 v12, 0
	v_mov_b32_e32 v13, 0
	v_mov_b32_e32 v14, 0
	v_mov_b32_e32 v15, 0
	v_mov_b32_e32 v16, 0
	v_mov_b32_e32 v17, 0
	v_mov_b32_e32 v18, 0
	v_mov_b32_e32 v19, 0
	v_mov_b32_e32 v20, 0
	v_mov_b32_e32 v21, 0
	v_mov_b32_e32 v22, 0
	v_mov_b32_e32 v23, 0
	v_mov_b32_e32 v24, 0
	v_mov_b32_e32 v25, 0
	v_mov_b32_e32 v26, 0
	v_mov_b32_e32 v27, 0
	v_mov_b32_e32 v28, 0
	v_mov_b32_e32 v29, 0
	v_mov_b32_e32 v30, 0
	v_mov_b32_e32 v31, 0
	v_mov_b32_e32 v32, 0
	v_mov_b32_e32 v33, 0
	v_mov_b32_e32 v34, 0
	v_mov_b32_e32 v35, 0
	v_mov_b32_e32 v36, 0
	v_mov_b32_e32 v37, 0
	v_mov_b32_e32 v38, 0
	v_mov_b32_e32 v39, 0
	v_mov_b32_e32 v40, 0
	v_mov_b32_e32 v41, 0
	v_mov_b32_e32 v42, 0
	v_mov_b32_e32 v43, 0
	v_mov_b32_e32 v44, 0
	v_mov_b32_e32 v45, 0
	v_mov_b32_e32 v46, 0
	v_mov_b32_e32 v47, 0
	v_mov_b32_e32 v48, 0
	v_mov_b32_e32 v49, 0
	v_mov_b32_e32 v50, 0
	v_mov_b32_e32 v51, 0
	v_mov_b32_e32 v52, 0
	v_mov_b32_e32 v53, 0
	v_mov_b32_e32 v54, 0
	v_mov_b32_e32 v55, 0
	v_mov_b32_e32 v56, 0
	v_mov_b32_e32 v57, 0
	v_mov_b32_e32 v58, 0
	v_mov_b32_e32 v59, 0
	v_mov_b32_e32 v60, 0
	v_mov_b32_e32 v61, 0
	v_mov_b32_e32 v62, 0
	v_mov_b32_e32 v63, 0
	v_mov_b32_e32 v64, 0
	v_mov_b32_e32 v65, 0
	v_mov_b32_e32 v66, 0
	v_mov_b32_e32 v67, 0
	v_mov_b32_e32 v68, 0
	v_mov_b32_e32 v69, 0
	v_mov_b32_e32 v70, 0
	v_mov_b32_e32 v71, 0
	v_mov_b32_e32 v72, 0
	v_mov_b32_e32 v73, 0
	v_mov_b32_e32 v74, 0
	v_mov_b32_e32 v75, 0
	v_mov_b32_e32 v76, 0
	v_mov_b32_e32 v77, 0
	v_mov_b32_e32 v78, 0
	v_mov_b32_e32 v79, 0
	v_mov_b32_e32 v80, 0
	v_mov_b32_e32 v81, 0
	v_mov_b32_e32 v82, 0
	v_mov_b32_e32 v83, 0
	v_mov_b32_e32 v84, 0
	v_mov_b32_e32 v85, 0
	v_mov_b32_e32 v86, 0
	v_mov_b32_e32 v87, 0
	v_mov_b32_e32 v88, 0
	v_mov_b32_e32 v89, 0
	v_mov_b32_e32 v90, 0
	v_mov_b32_e32 v91, 0
	v_mov_b32_e32 v92, 0
	v_mov_b32_e32 v93, 0
	v_mov_b32_e32 v94, 0
	v_mov_b32_e32 v95, 0
	v_mov_b32_e32 v96, 0
	v_mov_b32_e32 v97, 0
	v_mov_b32_e32 v98, 0
	v_mov_b32_e32 v99, 0
	v_mov_b32_e32 v100, 0
	v_mov_b32_e32 v101, 0
	v_mov_b32_e32 v102, 0
	v_mov_b32_e32 v103, 0
	v_mov_b32_e32 v104, 0
	v_mov_b32_e32 v105, 0
	v_mov_b32_e32 v106, 0
	v_mov_b32_e32 v107, 0
	v_mov_b32_e32 v108, 0
	v_mov_b32_e32 v109, 0
	v_mov_b32_e32 v110, 0
	v_mov_b32_e32 v111, 0
	v_mov_b32_e32 v112, 0
	v_mov_b32_e32 v113, 0
	v_mov_b32_e32 v114, 0
	v_mov_b32_e32 v115, 0
	v_mov_b32_e32 v116, 0
	v_mov_b32_e32 v117, 0
	v_mov_b32_e32 v118, 0
	v_mov_b32_e32 v119, 0
	v_mov_b32_e32 v120, 0
	v_mov_b32_e32 v121, 0
	v_mov_b32_e32 v122, 0
	v_mov_b32_e32 v123, 0
	v_mov_b32_e32 v124, 0
	v_mov_b32_e32 v125, 0
	v_mov_b32_e32 v126, 0
	v_mov_b32_e32 v127, 0
	v_mov_b32_e32 v128, 0
	v_mov_b32_e32 v129, 0
	v_mov_b32_e32 v130, 0
	v_mov_b32_e32 v131, 0
	v_mov_b32_e32 v132, 0
	v_mov_b32_e32 v133, 0
	v_mov_b32_e32 v134, 0
	v_mov_b32_e32 v135, 0
	s_mov_b32 s63, 0
	s_waitcnt vmcnt(0)
	s_barrier
	s_add_u32 s56, s56, 0x80
	s_addc_u32 s57, s57, 0
	s_add_u32 m0, s62, 0x8800
	s_add_u32 s4, s56, 0x0
	s_addc_u32 s5, s57, 0
	global_load_lds_dwordx4 v162, s[4:5]
	s_add_u32 m0, s62, 0x9800
	s_add_u32 s4, s56, 0x10000
	s_addc_u32 s5, s57, 0
	global_load_lds_dwordx4 v162, s[4:5]
	s_add_u32 m0, s62, 0xa800
	s_add_u32 s4, s56, 0x20000
	s_addc_u32 s5, s57, 0
	global_load_lds_dwordx4 v162, s[4:5]
	s_add_u32 m0, s62, 0xb800
	s_add_u32 s4, s56, 0x30000
	s_addc_u32 s5, s57, 0
	global_load_lds_dwordx4 v162, s[4:5]
	s_add_u32 m0, s62, 0xc800
	s_add_u32 s4, s56, 0x40000
	s_addc_u32 s5, s57, 0
	global_load_lds_dwordx4 v162, s[4:5]
	s_add_u32 m0, s62, 0xd800
	s_add_u32 s4, s56, 0x50000
	s_addc_u32 s5, s57, 0
	global_load_lds_dwordx4 v162, s[4:5]
	s_add_u32 m0, s62, 0xe800
	s_add_u32 s4, s56, 0x60000
	s_addc_u32 s5, s57, 0
	global_load_lds_dwordx4 v162, s[4:5]
	s_add_u32 m0, s62, 0xf800
	s_add_u32 s4, s56, 0x70000
	s_addc_u32 s5, s57, 0
	global_load_lds_dwordx4 v162, s[4:5]
	s_cmp_gt_u32 s70, 1
	s_cbranch_scc1 .Lg2_ff1_nodma_1
	s_add_u32 m0, s62, 0x10800
	s_add_u32 s4, s56, 0x80000
	s_addc_u32 s5, s57, 0
	global_load_lds_dwordx4 v162, s[4:5]

.Lg2_ff1_loop17:
	s_add_u32 s58, s58, 0x800
	s_addc_u32 s59, s59, 0
	global_load_dwordx4 v[200:203], v160, s[58:59] offset:0
	global_load_dwordx4 v[204:207], v160, s[58:59] offset:1024
	global_load_dwordx4 v[208:211], v161, s[58:59] offset:0
	global_load_dwordx4 v[240:243], v161, s[58:59] offset:1024
	ds_read_b128 v[164:167], v156 offset:8192
	ds_read_b128 v[168:171], v156 offset:10240
	ds_read_b128 v[172:175], v156 offset:12288
	ds_read_b128 v[176:179], v156 offset:14336
	s_waitcnt lgkmcnt(4)
	v_mfma_f32_16x16x32_bf16 v[0:3], v[184:187], v[136:139], v[0:3]
	v_mfma_f32_16x16x32_bf16 v[4:7], v[192:195], v[136:139], v[4:7]
	v_mfma_f32_16x16x32_bf16 v[8:11], v[184:187], v[140:143], v[8:11]
	v_mfma_f32_16x16x32_bf16 v[12:15], v[192:195], v[140:143], v[12:15]
	v_mfma_f32_16x16x32_bf16 v[16:19], v[184:187], v[144:147], v[16:19]
	v_mfma_f32_16x16x32_bf16 v[20:23], v[192:195], v[144:147], v[20:23]
	v_mfma_f32_16x16x32_bf16 v[24:27], v[184:187], v[148:151], v[24:27]
	v_mfma_f32_16x16x32_bf16 v[28:31], v[192:195], v[148:151], v[28:31]
	ds_read_b128 v[136:139], v156 offset:16384
	ds_read_b128 v[140:143], v156 offset:18432
	ds_read_b128 v[144:147], v156 offset:20480
	ds_read_b128 v[148:151], v156 offset:22528
	s_waitcnt lgkmcnt(4)
	v_mfma_f32_16x16x32_bf16 v[32:35], v[184:187], v[164:167], v[32:35]
	v_mfma_f32_16x16x32_bf16 v[36:39], v[192:195], v[164:167], v[36:39]
	v_mfma_f32_16x16x32_bf16 v[40:43], v[184:187], v[168:171], v[40:43]
	v_mfma_f32_16x16x32_bf16 v[44:47], v[192:195], v[168:171], v[44:47]
	v_mfma_f32_16x16x32_bf16 v[48:51], v[184:187], v[172:175], v[48:51]
	v_mfma_f32_16x16x32_bf16 v[52:55], v[192:195], v[172:175], v[52:55]
	v_mfma_f32_16x16x32_bf16 v[56:59], v[184:187], v[176:179], v[56:59]
	v_mfma_f32_16x16x32_bf16 v[60:63], v[192:195], v[176:179], v[60:63]
	ds_read_b128 v[164:167], v156 offset:24576
	ds_read_b128 v[168:171], v156 offset:26624
	ds_read_b128 v[172:175], v156 offset:28672
	ds_read_b128 v[176:179], v156 offset:30720
	ds_read_b128 v[180:183], v156 offset:32768
	s_waitcnt lgkmcnt(5)
	v_mfma_f32_16x16x32_bf16 v[64:67], v[184:187], v[136:139], v[64:67]
	v_mfma_f32_16x16x32_bf16 v[68:71], v[192:195], v[136:139], v[68:71]
	v_mfma_f32_16x16x32_bf16 v[72:75], v[184:187], v[140:143], v[72:75]
	v_mfma_f32_16x16x32_bf16 v[76:79], v[192:195], v[140:143], v[76:79]
	v_mfma_f32_16x16x32_bf16 v[80:83], v[184:187], v[144:147], v[80:83]
	v_mfma_f32_16x16x32_bf16 v[84:87], v[192:195], v[144:147], v[84:87]
	v_mfma_f32_16x16x32_bf16 v[88:91], v[184:187], v[148:151], v[88:91]
	v_mfma_f32_16x16x32_bf16 v[92:95], v[192:195], v[148:151], v[92:95]
	ds_read_b128 v[136:139], v157 offset:0
	ds_read_b128 v[140:143], v157 offset:2048
	ds_read_b128 v[144:147], v157 offset:4096
	ds_read_b128 v[148:151], v157 offset:6144
	s_waitcnt lgkmcnt(4)
	v_mfma_f32_16x16x32_bf16 v[96:99], v[184:187], v[164:167], v[96:99]
	v_mfma_f32_16x16x32_bf16 v[100:103], v[192:195], v[164:167], v[100:103]
	v_mfma_f32_16x16x32_bf16 v[104:107], v[184:187], v[168:171], v[104:107]
	v_mfma_f32_16x16x32_bf16 v[108:111], v[192:195], v[168:171], v[108:111]
	v_mfma_f32_16x16x32_bf16 v[112:115], v[184:187], v[172:175], v[112:115]
	v_mfma_f32_16x16x32_bf16 v[116:119], v[192:195], v[172:175], v[116:119]
	v_mfma_f32_16x16x32_bf16 v[120:123], v[184:187], v[176:179], v[120:123]
	v_mfma_f32_16x16x32_bf16 v[124:127], v[192:195], v[176:179], v[124:127]
	v_mfma_f32_16x16x32_bf16 v[128:131], v[184:187], v[180:183], v[128:131]
	v_mfma_f32_16x16x32_bf16 v[132:135], v[192:195], v[180:183], v[132:135]
	ds_read_b128 v[164:167], v157 offset:8192
	ds_read_b128 v[168:171], v157 offset:10240
	ds_read_b128 v[172:175], v157 offset:12288
	ds_read_b128 v[176:179], v157 offset:14336
	s_waitcnt lgkmcnt(4)
	v_mfma_f32_16x16x32_bf16 v[0:3], v[188:191], v[136:139], v[0:3]
	v_mfma_f32_16x16x32_bf16 v[4:7], v[196:199], v[136:139], v[4:7]
	v_mfma_f32_16x16x32_bf16 v[8:11], v[188:191], v[140:143], v[8:11]
	v_mfma_f32_16x16x32_bf16 v[12:15], v[196:199], v[140:143], v[12:15]
	v_mfma_f32_16x16x32_bf16 v[16:19], v[188:191], v[144:147], v[16:19]
	v_mfma_f32_16x16x32_bf16 v[20:23], v[196:199], v[144:147], v[20:23]
	v_mfma_f32_16x16x32_bf16 v[24:27], v[188:191], v[148:151], v[24:27]
	v_mfma_f32_16x16x32_bf16 v[28:31], v[196:199], v[148:151], v[28:31]
	ds_read_b128 v[136:139], v157 offset:16384
	ds_read_b128 v[140:143], v157 offset:18432
	ds_read_b128 v[144:147], v157 offset:20480
	ds_read_b128 v[148:151], v157 offset:22528
	s_waitcnt lgkmcnt(4)
	v_mfma_f32_16x16x32_bf16 v[32:35], v[188:191], v[164:167], v[32:35]
	v_mfma_f32_16x16x32_bf16 v[36:39], v[196:199], v[164:167], v[36:39]
	v_mfma_f32_16x16x32_bf16 v[40:43], v[188:191], v[168:171], v[40:43]
	v_mfma_f32_16x16x32_bf16 v[44:47], v[196:199], v[168:171], v[44:47]
	v_mfma_f32_16x16x32_bf16 v[48:51], v[188:191], v[172:175], v[48:51]
	v_mfma_f32_16x16x32_bf16 v[52:55], v[196:199], v[172:175], v[52:55]
	v_mfma_f32_16x16x32_bf16 v[56:59], v[188:191], v[176:179], v[56:59]
	v_mfma_f32_16x16x32_bf16 v[60:63], v[196:199], v[176:179], v[60:63]
	ds_read_b128 v[164:167], v157 offset:24576
	ds_read_b128 v[168:171], v157 offset:26624
	ds_read_b128 v[172:175], v157 offset:28672
	ds_read_b128 v[176:179], v157 offset:30720
	ds_read_b128 v[180:183], v157 offset:32768
	s_waitcnt lgkmcnt(5)
	v_mfma_f32_16x16x32_bf16 v[64:67], v[188:191], v[136:139], v[64:67]
	v_mfma_f32_16x16x32_bf16 v[68:71], v[196:199], v[136:139], v[68:71]
	v_mfma_f32_16x16x32_bf16 v[72:75], v[188:191], v[140:143], v[72:75]
	v_mfma_f32_16x16x32_bf16 v[76:79], v[196:199], v[140:143], v[76:79]
	v_mfma_f32_16x16x32_bf16 v[80:83], v[188:191], v[144:147], v[80:83]
	v_mfma_f32_16x16x32_bf16 v[84:87], v[196:199], v[144:147], v[84:87]
	v_mfma_f32_16x16x32_bf16 v[88:91], v[188:191], v[148:151], v[88:91]
	v_mfma_f32_16x16x32_bf16 v[92:95], v[196:199], v[148:151], v[92:95]
	s_waitcnt vmcnt(0) lgkmcnt(0)
	s_barrier
	s_cmp_ge_u32 s63, 14
	s_cbranch_scc1 .Lg2_ff1_nd17_0
	s_add_u32 s56, s56, 0x80
	s_addc_u32 s57, s57, 0
	s_add_u32 m0, s62, 0x0
	s_add_u32 s4, s56, 0x0
	s_addc_u32 s5, s57, 0
	global_load_lds_dwordx4 v162, s[4:5]
	s_add_u32 m0, s62, 0x1000
	s_add_u32 s4, s56, 0x10000
	s_addc_u32 s5, s57, 0
	global_load_lds_dwordx4 v162, s[4:5]
	s_add_u32 m0, s62, 0x2000
	s_add_u32 s4, s56, 0x20000
	s_addc_u32 s5, s57, 0
	global_load_lds_dwordx4 v162, s[4:5]
	s_add_u32 m0, s62, 0x3000
	s_add_u32 s4, s56, 0x30000
	s_addc_u32 s5, s57, 0
	global_load_lds_dwordx4 v162, s[4:5]
	s_add_u32 m0, s62, 0x4000
	s_add_u32 s4, s56, 0x40000
	s_addc_u32 s5, s57, 0
	global_load_lds_dwordx4 v162, s[4:5]
	s_add_u32 m0, s62, 0x5000
	s_add_u32 s4, s56, 0x50000
	s_addc_u32 s5, s57, 0
	global_load_lds_dwordx4 v162, s[4:5]
	s_add_u32 m0, s62, 0x6000
	s_add_u32 s4, s56, 0x60000
	s_addc_u32 s5, s57, 0
	global_load_lds_dwordx4 v162, s[4:5]
	s_add_u32 m0, s62, 0x7000
	s_add_u32 s4, s56, 0x70000
	s_addc_u32 s5, s57, 0
	global_load_lds_dwordx4 v162, s[4:5]
	s_cmp_gt_u32 s70, 1
	s_cbranch_scc1 .Lg2_ff1_nodma_2
	s_add_u32 m0, s62, 0x8000
	s_add_u32 s4, s56, 0x80000
	s_addc_u32 s5, s57, 0
	global_load_lds_dwordx4 v162, s[4:5]
.Lg2_ff1_nodma_2:
.Lg2_ff1_nd17_0:
	ds_read_b128 v[136:139], v158 offset:0
	ds_read_b128 v[140:143], v158 offset:2048
	ds_read_b128 v[144:147], v158 offset:4096
	ds_read_b128 v[148:151], v158 offset:6144
	v_mfma_f32_16x16x32_bf16 v[96:99], v[188:191], v[164:167], v[96:99]
	v_mfma_f32_16x16x32_bf16 v[100:103], v[196:199], v[164:167], v[100:103]
	v_mfma_f32_16x16x32_bf16 v[104:107], v[188:191], v[168:171], v[104:107]
	v_mfma_f32_16x16x32_bf16 v[108:111], v[196:199], v[168:171], v[108:111]
	v_mfma_f32_16x16x32_bf16 v[112:115], v[188:191], v[172:175], v[112:115]
	v_mfma_f32_16x16x32_bf16 v[116:119], v[196:199], v[172:175], v[116:119]
	v_mfma_f32_16x16x32_bf16 v[120:123], v[188:191], v[176:179], v[120:123]
	v_mfma_f32_16x16x32_bf16 v[124:127], v[196:199], v[176:179], v[124:127]
	v_mfma_f32_16x16x32_bf16 v[128:131], v[188:191], v[180:183], v[128:131]
	v_mfma_f32_16x16x32_bf16 v[132:135], v[196:199], v[180:183], v[132:135]
	s_cmp_ge_u32 s63, 14
	s_cbranch_scc1 .Lg2_ff1_nb17_1
	s_add_u32 s58, s58, 0x800
	s_addc_u32 s59, s59, 0
	global_load_dwordx4 v[184:187], v160, s[58:59] offset:0
	global_load_dwordx4 v[188:191], v160, s[58:59] offset:1024
	global_load_dwordx4 v[192:195], v161, s[58:59] offset:0
	global_load_dwordx4 v[196:199], v161, s[58:59] offset:1024
.Lg2_ff1_nb17_1:
	ds_read_b128 v[164:167], v158 offset:8192
	ds_read_b128 v[168:171], v158 offset:10240
	ds_read_b128 v[172:175], v158 offset:12288
	ds_read_b128 v[176:179], v158 offset:14336
	s_waitcnt lgkmcnt(4)
	v_mfma_f32_16x16x32_bf16 v[0:3], v[200:203], v[136:139], v[0:3]
	v_mfma_f32_16x16x32_bf16 v[4:7], v[208:211], v[136:139], v[4:7]
	v_mfma_f32_16x16x32_bf16 v[8:11], v[200:203], v[140:143], v[8:11]
	v_mfma_f32_16x16x32_bf16 v[12:15], v[208:211], v[140:143], v[12:15]
	v_mfma_f32_16x16x32_bf16 v[16:19], v[200:203], v[144:147], v[16:19]
	v_mfma_f32_16x16x32_bf16 v[20:23], v[208:211], v[144:147], v[20:23]
	v_mfma_f32_16x16x32_bf16 v[24:27], v[200:203], v[148:151], v[24:27]
	v_mfma_f32_16x16x32_bf16 v[28:31], v[208:211], v[148:151], v[28:31]
	ds_read_b128 v[136:139], v158 offset:16384
	ds_read_b128 v[140:143], v158 offset:18432
	ds_read_b128 v[144:147], v158 offset:20480
	ds_read_b128 v[148:151], v158 offset:22528
	s_waitcnt lgkmcnt(4)
	v_mfma_f32_16x16x32_bf16 v[32:35], v[200:203], v[164:167], v[32:35]
	v_mfma_f32_16x16x32_bf16 v[36:39], v[208:211], v[164:167], v[36:39]
	v_mfma_f32_16x16x32_bf16 v[40:43], v[200:203], v[168:171], v[40:43]
	v_mfma_f32_16x16x32_bf16 v[44:47], v[208:211], v[168:171], v[44:47]
	v_mfma_f32_16x16x32_bf16 v[48:51], v[200:203], v[172:175], v[48:51]
	v_mfma_f32_16x16x32_bf16 v[52:55], v[208:211], v[172:175], v[52:55]
	v_mfma_f32_16x16x32_bf16 v[56:59], v[200:203], v[176:179], v[56:59]
	v_mfma_f32_16x16x32_bf16 v[60:63], v[208:211], v[176:179], v[60:63]
	ds_read_b128 v[164:167], v158 offset:24576
	ds_read_b128 v[168:171], v158 offset:26624
	ds_read_b128 v[172:175], v158 offset:28672
	ds_read_b128 v[176:179], v158 offset:30720
	ds_read_b128 v[180:183], v158 offset:32768
	s_waitcnt lgkmcnt(5)
	v_mfma_f32_16x16x32_bf16 v[64:67], v[200:203], v[136:139], v[64:67]
	v_mfma_f32_16x16x32_bf16 v[68:71], v[208:211], v[136:139], v[68:71]
	v_mfma_f32_16x16x32_bf16 v[72:75], v[200:203], v[140:143], v[72:75]
	v_mfma_f32_16x16x32_bf16 v[76:79], v[208:211], v[140:143], v[76:79]
	v_mfma_f32_16x16x32_bf16 v[80:83], v[200:203], v[144:147], v[80:83]
	v_mfma_f32_16x16x32_bf16 v[84:87], v[208:211], v[144:147], v[84:87]
	v_mfma_f32_16x16x32_bf16 v[88:91], v[200:203], v[148:151], v[88:91]
	v_mfma_f32_16x16x32_bf16 v[92:95], v[208:211], v[148:151], v[92:95]
	ds_read_b128 v[136:139], v159 offset:0
	ds_read_b128 v[140:143], v159 offset:2048
	ds_read_b128 v[144:147], v159 offset:4096
	ds_read_b128 v[148:151], v159 offset:6144
	s_waitcnt lgkmcnt(4)
	v_mfma_f32_16x16x32_bf16 v[96:99], v[200:203], v[164:167], v[96:99]
	v_mfma_f32_16x16x32_bf16 v[100:103], v[208:211], v[164:167], v[100:103]
	v_mfma_f32_16x16x32_bf16 v[104:107], v[200:203], v[168:171], v[104:107]
	v_mfma_f32_16x16x32_bf16 v[108:111], v[208:211], v[168:171], v[108:111]
	v_mfma_f32_16x16x32_bf16 v[112:115], v[200:203], v[172:175], v[112:115]
	v_mfma_f32_16x16x32_bf16 v[116:119], v[208:211], v[172:175], v[116:119]
	v_mfma_f32_16x16x32_bf16 v[120:123], v[200:203], v[176:179], v[120:123]
	v_mfma_f32_16x16x32_bf16 v[124:127], v[208:211], v[176:179], v[124:127]
	v_mfma_f32_16x16x32_bf16 v[128:131], v[200:203], v[180:183], v[128:131]
	v_mfma_f32_16x16x32_bf16 v[132:135], v[208:211], v[180:183], v[132:135]
	ds_read_b128 v[164:167], v159 offset:8192
	ds_read_b128 v[168:171], v159 offset:10240
	ds_read_b128 v[172:175], v159 offset:12288
	ds_read_b128 v[176:179], v159 offset:14336
	s_waitcnt lgkmcnt(4)
	v_mfma_f32_16x16x32_bf16 v[0:3], v[204:207], v[136:139], v[0:3]
	v_mfma_f32_16x16x32_bf16 v[4:7], v[240:243], v[136:139], v[4:7]
	v_mfma_f32_16x16x32_bf16 v[8:11], v[204:207], v[140:143], v[8:11]
	v_mfma_f32_16x16x32_bf16 v[12:15], v[240:243], v[140:143], v[12:15]
	v_mfma_f32_16x16x32_bf16 v[16:19], v[204:207], v[144:147], v[16:19]
	v_mfma_f32_16x16x32_bf16 v[20:23], v[240:243], v[144:147], v[20:23]
	v_mfma_f32_16x16x32_bf16 v[24:27], v[204:207], v[148:151], v[24:27]
	v_mfma_f32_16x16x32_bf16 v[28:31], v[240:243], v[148:151], v[28:31]
	ds_read_b128 v[136:139], v159 offset:16384
	ds_read_b128 v[140:143], v159 offset:18432
	ds_read_b128 v[144:147], v159 offset:20480
	ds_read_b128 v[148:151], v159 offset:22528
	s_waitcnt lgkmcnt(4)
	v_mfma_f32_16x16x32_bf16 v[32:35], v[204:207], v[164:167], v[32:35]
	v_mfma_f32_16x16x32_bf16 v[36:39], v[240:243], v[164:167], v[36:39]
	v_mfma_f32_16x16x32_bf16 v[40:43], v[204:207], v[168:171], v[40:43]
	v_mfma_f32_16x16x32_bf16 v[44:47], v[240:243], v[168:171], v[44:47]
	v_mfma_f32_16x16x32_bf16 v[48:51], v[204:207], v[172:175], v[48:51]
	v_mfma_f32_16x16x32_bf16 v[52:55], v[240:243], v[172:175], v[52:55]
	v_mfma_f32_16x16x32_bf16 v[56:59], v[204:207], v[176:179], v[56:59]
	v_mfma_f32_16x16x32_bf16 v[60:63], v[240:243], v[176:179], v[60:63]
	ds_read_b128 v[164:167], v159 offset:24576
	ds_read_b128 v[168:171], v159 offset:26624
	ds_read_b128 v[172:175], v159 offset:28672
	ds_read_b128 v[176:179], v159 offset:30720
	ds_read_b128 v[180:183], v159 offset:32768
	s_waitcnt lgkmcnt(5)
	v_mfma_f32_16x16x32_bf16 v[64:67], v[204:207], v[136:139], v[64:67]
	v_mfma_f32_16x16x32_bf16 v[68:71], v[240:243], v[136:139], v[68:71]
	v_mfma_f32_16x16x32_bf16 v[72:75], v[204:207], v[140:143], v[72:75]
	v_mfma_f32_16x16x32_bf16 v[76:79], v[240:243], v[140:143], v[76:79]
	v_mfma_f32_16x16x32_bf16 v[80:83], v[204:207], v[144:147], v[80:83]
	v_mfma_f32_16x16x32_bf16 v[84:87], v[240:243], v[144:147], v[84:87]
	v_mfma_f32_16x16x32_bf16 v[88:91], v[204:207], v[148:151], v[88:91]
	v_mfma_f32_16x16x32_bf16 v[92:95], v[240:243], v[148:151], v[92:95]
	s_waitcnt vmcnt(0) lgkmcnt(0)
	s_barrier
	s_cmp_ge_u32 s63, 14
	s_cbranch_scc1 .Lg2_ff1_nd17_1
	s_add_u32 s56, s56, 0x80
	s_addc_u32 s57, s57, 0
	s_add_u32 m0, s62, 0x8800
	s_add_u32 s4, s56, 0x0
	s_addc_u32 s5, s57, 0
	global_load_lds_dwordx4 v162, s[4:5]
	s_add_u32 m0, s62, 0x9800
	s_add_u32 s4, s56, 0x10000
	s_addc_u32 s5, s57, 0
	global_load_lds_dwordx4 v162, s[4:5]
	s_add_u32 m0, s62, 0xa800
	s_add_u32 s4, s56, 0x20000
	s_addc_u32 s5, s57, 0
	global_load_lds_dwordx4 v162, s[4:5]
	s_add_u32 m0, s62, 0xb800
	s_add_u32 s4, s56, 0x30000
	s_addc_u32 s5, s57, 0
	global_load_lds_dwordx4 v162, s[4:5]
	s_add_u32 m0, s62, 0xc800
	s_add_u32 s4, s56, 0x40000
	s_addc_u32 s5, s57, 0
	global_load_lds_dwordx4 v162, s[4:5]
	s_add_u32 m0, s62, 0xd800
	s_add_u32 s4, s56, 0x50000
	s_addc_u32 s5, s57, 0
	global_load_lds_dwordx4 v162, s[4:5]
	s_add_u32 m0, s62, 0xe800
	s_add_u32 s4, s56, 0x60000
	s_addc_u32 s5, s57, 0
	global_load_lds_dwordx4 v162, s[4:5]
	s_add_u32 m0, s62, 0xf800
	s_add_u32 s4, s56, 0x70000
	s_addc_u32 s5, s57, 0
	global_load_lds_dwordx4 v162, s[4:5]
	s_cmp_gt_u32 s70, 1
	s_cbranch_scc1 .Lg2_ff1_nodma_3
	s_add_u32 m0, s62, 0x10800
	s_add_u32 s4, s56, 0x80000
	s_addc_u32 s5, s57, 0
	global_load_lds_dwordx4 v162, s[4:5]

.Lg2_ff1_nd17_1:
	v_mfma_f32_16x16x32_bf16 v[96:99], v[204:207], v[164:167], v[96:99]
	v_mfma_f32_16x16x32_bf16 v[100:103], v[240:243], v[164:167], v[100:103]
	v_mfma_f32_16x16x32_bf16 v[104:107], v[204:207], v[168:171], v[104:107]
	v_mfma_f32_16x16x32_bf16 v[108:111], v[240:243], v[168:171], v[108:111]
	v_mfma_f32_16x16x32_bf16 v[112:115], v[204:207], v[172:175], v[112:115]
	v_mfma_f32_16x16x32_bf16 v[116:119], v[240:243], v[172:175], v[116:119]
	v_mfma_f32_16x16x32_bf16 v[120:123], v[204:207], v[176:179], v[120:123]
	v_mfma_f32_16x16x32_bf16 v[124:127], v[240:243], v[176:179], v[124:127]
	v_mfma_f32_16x16x32_bf16 v[128:131], v[204:207], v[180:183], v[128:131]
	v_mfma_f32_16x16x32_bf16 v[132:135], v[240:243], v[180:183], v[132:135]
	s_add_i32 s63, s63, 2
	s_cmp_lt_u32 s63, 16
	s_cbranch_scc1 .Lg2_ff1_loop17
	s_branch .Lg2_ff1_episel
.Lg2_ff1_k16:
	s_add_u32 m0, s62, 0x0
	s_add_u32 s4, s56, 0x0
	s_addc_u32 s5, s57, 0
	global_load_lds_dwordx4 v162, s[4:5]
	s_add_u32 m0, s62, 0x1000
	s_add_u32 s4, s56, 0x10000
	s_addc_u32 s5, s57, 0
	global_load_lds_dwordx4 v162, s[4:5]
	s_add_u32 m0, s62, 0x2000
	s_add_u32 s4, s56, 0x20000
	s_addc_u32 s5, s57, 0
	global_load_lds_dwordx4 v162, s[4:5]
	s_add_u32 m0, s62, 0x3000
	s_add_u32 s4, s56, 0x30000
	s_addc_u32 s5, s57, 0
	global_load_lds_dwordx4 v162, s[4:5]
	s_add_u32 m0, s62, 0x4000
	s_add_u32 s4, s56, 0x40000
	s_addc_u32 s5, s57, 0
	global_load_lds_dwordx4 v162, s[4:5]
	s_add_u32 m0, s62, 0x5000
	s_add_u32 s4, s56, 0x50000
	s_addc_u32 s5, s57, 0
	global_load_lds_dwordx4 v162, s[4:5]
	s_add_u32 m0, s62, 0x6000
	s_add_u32 s4, s56, 0x60000
	s_addc_u32 s5, s57, 0
	global_load_lds_dwordx4 v162, s[4:5]
	s_add_u32 m0, s62, 0x7000
	s_add_u32 s4, s56, 0x70000
	s_addc_u32 s5, s57, 0
	global_load_lds_dwordx4 v162, s[4:5]
	global_load_dwordx4 v[184:187], v160, s[58:59] offset:0
	global_load_dwordx4 v[188:191], v160, s[58:59] offset:1024
	global_load_dwordx4 v[192:195], v161, s[58:59] offset:0
	global_load_dwordx4 v[196:199], v161, s[58:59] offset:1024
	v_mov_b32_e32 v0, 0
	v_mov_b32_e32 v1, 0
	v_mov_b32_e32 v2, 0
	v_mov_b32_e32 v3, 0
	v_mov_b32_e32 v4, 0
	v_mov_b32_e32 v5, 0
	v_mov_b32_e32 v6, 0
	v_mov_b32_e32 v7, 0
	v_mov_b32_e32 v8, 0
	v_mov_b32_e32 v9, 0
	v_mov_b32_e32 v10, 0
	v_mov_b32_e32 v11, 0
	v_mov_b32_e32 v12, 0
	v_mov_b32_e32 v13, 0
	v_mov_b32_e32 v14, 0
	v_mov_b32_e32 v15, 0
	v_mov_b32_e32 v16, 0
	v_mov_b32_e32 v17, 0
	v_mov_b32_e32 v18, 0
	v_mov_b32_e32 v19, 0
	v_mov_b32_e32 v20, 0
	v_mov_b32_e32 v21, 0
	v_mov_b32_e32 v22, 0
	v_mov_b32_e32 v23, 0
	v_mov_b32_e32 v24, 0
	v_mov_b32_e32 v25, 0
	v_mov_b32_e32 v26, 0
	v_mov_b32_e32 v27, 0
	v_mov_b32_e32 v28, 0
	v_mov_b32_e32 v29, 0
	v_mov_b32_e32 v30, 0
	v_mov_b32_e32 v31, 0
	v_mov_b32_e32 v32, 0
	v_mov_b32_e32 v33, 0
	v_mov_b32_e32 v34, 0
	v_mov_b32_e32 v35, 0
	v_mov_b32_e32 v36, 0
	v_mov_b32_e32 v37, 0
	v_mov_b32_e32 v38, 0
	v_mov_b32_e32 v39, 0
	v_mov_b32_e32 v40, 0
	v_mov_b32_e32 v41, 0
	v_mov_b32_e32 v42, 0
	v_mov_b32_e32 v43, 0
	v_mov_b32_e32 v44, 0
	v_mov_b32_e32 v45, 0
	v_mov_b32_e32 v46, 0
	v_mov_b32_e32 v47, 0
	v_mov_b32_e32 v48, 0
	v_mov_b32_e32 v49, 0
	v_mov_b32_e32 v50, 0
	v_mov_b32_e32 v51, 0
	v_mov_b32_e32 v52, 0
	v_mov_b32_e32 v53, 0
	v_mov_b32_e32 v54, 0
	v_mov_b32_e32 v55, 0
	v_mov_b32_e32 v56, 0
	v_mov_b32_e32 v57, 0
	v_mov_b32_e32 v58, 0
	v_mov_b32_e32 v59, 0
	v_mov_b32_e32 v60, 0
	v_mov_b32_e32 v61, 0
	v_mov_b32_e32 v62, 0
	v_mov_b32_e32 v63, 0
	v_mov_b32_e32 v64, 0
	v_mov_b32_e32 v65, 0
	v_mov_b32_e32 v66, 0
	v_mov_b32_e32 v67, 0
	v_mov_b32_e32 v68, 0
	v_mov_b32_e32 v69, 0
	v_mov_b32_e32 v70, 0
	v_mov_b32_e32 v71, 0
	v_mov_b32_e32 v72, 0
	v_mov_b32_e32 v73, 0
	v_mov_b32_e32 v74, 0
	v_mov_b32_e32 v75, 0
	v_mov_b32_e32 v76, 0
	v_mov_b32_e32 v77, 0
	v_mov_b32_e32 v78, 0
	v_mov_b32_e32 v79, 0
	v_mov_b32_e32 v80, 0
	v_mov_b32_e32 v81, 0
	v_mov_b32_e32 v82, 0
	v_mov_b32_e32 v83, 0
	v_mov_b32_e32 v84, 0
	v_mov_b32_e32 v85, 0
	v_mov_b32_e32 v86, 0
	v_mov_b32_e32 v87, 0
	v_mov_b32_e32 v88, 0
	v_mov_b32_e32 v89, 0
	v_mov_b32_e32 v90, 0
	v_mov_b32_e32 v91, 0
	v_mov_b32_e32 v92, 0
	v_mov_b32_e32 v93, 0
	v_mov_b32_e32 v94, 0
	v_mov_b32_e32 v95, 0
	v_mov_b32_e32 v96, 0
	v_mov_b32_e32 v97, 0
	v_mov_b32_e32 v98, 0
	v_mov_b32_e32 v99, 0
	v_mov_b32_e32 v100, 0
	v_mov_b32_e32 v101, 0
	v_mov_b32_e32 v102, 0
	v_mov_b32_e32 v103, 0
	v_mov_b32_e32 v104, 0
	v_mov_b32_e32 v105, 0
	v_mov_b32_e32 v106, 0
	v_mov_b32_e32 v107, 0
	v_mov_b32_e32 v108, 0
	v_mov_b32_e32 v109, 0
	v_mov_b32_e32 v110, 0
	v_mov_b32_e32 v111, 0
	v_mov_b32_e32 v112, 0
	v_mov_b32_e32 v113, 0
	v_mov_b32_e32 v114, 0
	v_mov_b32_e32 v115, 0
	v_mov_b32_e32 v116, 0
	v_mov_b32_e32 v117, 0
	v_mov_b32_e32 v118, 0
	v_mov_b32_e32 v119, 0
	v_mov_b32_e32 v120, 0
	v_mov_b32_e32 v121, 0
	v_mov_b32_e32 v122, 0
	v_mov_b32_e32 v123, 0
	v_mov_b32_e32 v124, 0
	v_mov_b32_e32 v125, 0
	v_mov_b32_e32 v126, 0
	v_mov_b32_e32 v127, 0
	s_mov_b32 s63, 0
	s_waitcnt vmcnt(0)
	s_barrier
	s_add_u32 s56, s56, 0x80
	s_addc_u32 s57, s57, 0
	s_add_u32 m0, s62, 0x8800
	s_add_u32 s4, s56, 0x0
	s_addc_u32 s5, s57, 0
	global_load_lds_dwordx4 v162, s[4:5]
	s_add_u32 m0, s62, 0x9800
	s_add_u32 s4, s56, 0x10000
	s_addc_u32 s5, s57, 0
	global_load_lds_dwordx4 v162, s[4:5]
	s_add_u32 m0, s62, 0xa800
	s_add_u32 s4, s56, 0x20000
	s_addc_u32 s5, s57, 0
	global_load_lds_dwordx4 v162, s[4:5]
	s_add_u32 m0, s62, 0xb800
	s_add_u32 s4, s56, 0x30000
	s_addc_u32 s5, s57, 0
	global_load_lds_dwordx4 v162, s[4:5]
	s_add_u32 m0, s62, 0xc800
	s_add_u32 s4, s56, 0x40000
	s_addc_u32 s5, s57, 0
	global_load_lds_dwordx4 v162, s[4:5]
	s_add_u32 m0, s62, 0xd800
	s_add_u32 s4, s56, 0x50000
	s_addc_u32 s5, s57, 0
	global_load_lds_dwordx4 v162, s[4:5]
	s_add_u32 m0, s62, 0xe800
	s_add_u32 s4, s56, 0x60000
	s_addc_u32 s5, s57, 0
	global_load_lds_dwordx4 v162, s[4:5]
	s_add_u32 m0, s62, 0xf800
	s_add_u32 s4, s56, 0x70000
	s_addc_u32 s5, s57, 0
	global_load_lds_dwordx4 v162, s[4:5]
	ds_read_b128 v[136:139], v156 offset:0
	ds_read_b128 v[140:143], v156 offset:2048
	ds_read_b128 v[144:147], v156 offset:4096
	ds_read_b128 v[148:151], v156 offset:6144
.Lg2_ff1_loop16:
	s_add_u32 s58, s58, 0x800
	s_addc_u32 s59, s59, 0
	global_load_dwordx4 v[200:203], v160, s[58:59] offset:0
	global_load_dwordx4 v[204:207], v160, s[58:59] offset:1024
	global_load_dwordx4 v[208:211], v161, s[58:59] offset:0
	global_load_dwordx4 v[240:243], v161, s[58:59] offset:1024
	ds_read_b128 v[164:167], v156 offset:8192
	ds_read_b128 v[168:171], v156 offset:10240
	ds_read_b128 v[172:175], v156 offset:12288
	ds_read_b128 v[176:179], v156 offset:14336
	s_waitcnt lgkmcnt(4)
	v_mfma_f32_16x16x32_bf16 v[0:3], v[184:187], v[136:139], v[0:3]
	v_mfma_f32_16x16x32_bf16 v[4:7], v[192:195], v[136:139], v[4:7]
	v_mfma_f32_16x16x32_bf16 v[8:11], v[184:187], v[140:143], v[8:11]
	v_mfma_f32_16x16x32_bf16 v[12:15], v[192:195], v[140:143], v[12:15]
	v_mfma_f32_16x16x32_bf16 v[16:19], v[184:187], v[144:147], v[16:19]
	v_mfma_f32_16x16x32_bf16 v[20:23], v[192:195], v[144:147], v[20:23]
	v_mfma_f32_16x16x32_bf16 v[24:27], v[184:187], v[148:151], v[24:27]
	v_mfma_f32_16x16x32_bf16 v[28:31], v[192:195], v[148:151], v[28:31]
	ds_read_b128 v[136:139], v156 offset:16384
	ds_read_b128 v[140:143], v156 offset:18432
	ds_read_b128 v[144:147], v156 offset:20480
	ds_read_b128 v[148:151], v156 offset:22528
	s_waitcnt lgkmcnt(4)
	v_mfma_f32_16x16x32_bf16 v[32:35], v[184:187], v[164:167], v[32:35]
	v_mfma_f32_16x16x32_bf16 v[36:39], v[192:195], v[164:167], v[36:39]
	v_mfma_f32_16x16x32_bf16 v[40:43], v[184:187], v[168:171], v[40:43]
	v_mfma_f32_16x16x32_bf16 v[44:47], v[192:195], v[168:171], v[44:47]
	v_mfma_f32_16x16x32_bf16 v[48:51], v[184:187], v[172:175], v[48:51]
	v_mfma_f32_16x16x32_bf16 v[52:55], v[192:195], v[172:175], v[52:55]
	v_mfma_f32_16x16x32_bf16 v[56:59], v[184:187], v[176:179], v[56:59]
	v_mfma_f32_16x16x32_bf16 v[60:63], v[192:195], v[176:179], v[60:63]
	ds_read_b128 v[164:167], v156 offset:24576
	ds_read_b128 v[168:171], v156 offset:26624
	ds_read_b128 v[172:175], v156 offset:28672
	ds_read_b128 v[176:179], v156 offset:30720
	s_waitcnt lgkmcnt(4)
	v_mfma_f32_16x16x32_bf16 v[64:67], v[184:187], v[136:139], v[64:67]
	v_mfma_f32_16x16x32_bf16 v[68:71], v[192:195], v[136:139], v[68:71]
	v_mfma_f32_16x16x32_bf16 v[72:75], v[184:187], v[140:143], v[72:75]
	v_mfma_f32_16x16x32_bf16 v[76:79], v[192:195], v[140:143], v[76:79]
	v_mfma_f32_16x16x32_bf16 v[80:83], v[184:187], v[144:147], v[80:83]
	v_mfma_f32_16x16x32_bf16 v[84:87], v[192:195], v[144:147], v[84:87]
	v_mfma_f32_16x16x32_bf16 v[88:91], v[184:187], v[148:151], v[88:91]
	v_mfma_f32_16x16x32_bf16 v[92:95], v[192:195], v[148:151], v[92:95]
	ds_read_b128 v[136:139], v157 offset:0
	ds_read_b128 v[140:143], v157 offset:2048
	ds_read_b128 v[144:147], v157 offset:4096
	ds_read_b128 v[148:151], v157 offset:6144
	s_waitcnt lgkmcnt(4)
	v_mfma_f32_16x16x32_bf16 v[96:99], v[184:187], v[164:167], v[96:99]
	v_mfma_f32_16x16x32_bf16 v[100:103], v[192:195], v[164:167], v[100:103]
	v_mfma_f32_16x16x32_bf16 v[104:107], v[184:187], v[168:171], v[104:107]
	v_mfma_f32_16x16x32_bf16 v[108:111], v[192:195], v[168:171], v[108:111]
	v_mfma_f32_16x16x32_bf16 v[112:115], v[184:187], v[172:175], v[112:115]
	v_mfma_f32_16x16x32_bf16 v[116:119], v[192:195], v[172:175], v[116:119]
	v_mfma_f32_16x16x32_bf16 v[120:123], v[184:187], v[176:179], v[120:123]
	v_mfma_f32_16x16x32_bf16 v[124:127], v[192:195], v[176:179], v[124:127]
	ds_read_b128 v[164:167], v157 offset:8192
	ds_read_b128 v[168:171], v157 offset:10240
	ds_read_b128 v[172:175], v157 offset:12288
	ds_read_b128 v[176:179], v157 offset:14336
	s_waitcnt lgkmcnt(4)
	v_mfma_f32_16x16x32_bf16 v[0:3], v[188:191], v[136:139], v[0:3]
	v_mfma_f32_16x16x32_bf16 v[4:7], v[196:199], v[136:139], v[4:7]
	v_mfma_f32_16x16x32_bf16 v[8:11], v[188:191], v[140:143], v[8:11]
	v_mfma_f32_16x16x32_bf16 v[12:15], v[196:199], v[140:143], v[12:15]
	v_mfma_f32_16x16x32_bf16 v[16:19], v[188:191], v[144:147], v[16:19]
	v_mfma_f32_16x16x32_bf16 v[20:23], v[196:199], v[144:147], v[20:23]
	v_mfma_f32_16x16x32_bf16 v[24:27], v[188:191], v[148:151], v[24:27]
	v_mfma_f32_16x16x32_bf16 v[28:31], v[196:199], v[148:151], v[28:31]
	ds_read_b128 v[136:139], v157 offset:16384
	ds_read_b128 v[140:143], v157 offset:18432
	ds_read_b128 v[144:147], v157 offset:20480
	ds_read_b128 v[148:151], v157 offset:22528
	s_waitcnt lgkmcnt(4)
	v_mfma_f32_16x16x32_bf16 v[32:35], v[188:191], v[164:167], v[32:35]
	v_mfma_f32_16x16x32_bf16 v[36:39], v[196:199], v[164:167], v[36:39]
	v_mfma_f32_16x16x32_bf16 v[40:43], v[188:191], v[168:171], v[40:43]
	v_mfma_f32_16x16x32_bf16 v[44:47], v[196:199], v[168:171], v[44:47]
	v_mfma_f32_16x16x32_bf16 v[48:51], v[188:191], v[172:175], v[48:51]
	v_mfma_f32_16x16x32_bf16 v[52:55], v[196:199], v[172:175], v[52:55]
	v_mfma_f32_16x16x32_bf16 v[56:59], v[188:191], v[176:179], v[56:59]
	v_mfma_f32_16x16x32_bf16 v[60:63], v[196:199], v[176:179], v[60:63]
	ds_read_b128 v[164:167], v157 offset:24576
	ds_read_b128 v[168:171], v157 offset:26624
	ds_read_b128 v[172:175], v157 offset:28672
	ds_read_b128 v[176:179], v157 offset:30720
	s_waitcnt lgkmcnt(4)
	v_mfma_f32_16x16x32_bf16 v[64:67], v[188:191], v[136:139], v[64:67]
	v_mfma_f32_16x16x32_bf16 v[68:71], v[196:199], v[136:139], v[68:71]
	v_mfma_f32_16x16x32_bf16 v[72:75], v[188:191], v[140:143], v[72:75]
	v_mfma_f32_16x16x32_bf16 v[76:79], v[196:199], v[140:143], v[76:79]
	v_mfma_f32_16x16x32_bf16 v[80:83], v[188:191], v[144:147], v[80:83]
	v_mfma_f32_16x16x32_bf16 v[84:87], v[196:199], v[144:147], v[84:87]
	v_mfma_f32_16x16x32_bf16 v[88:91], v[188:191], v[148:151], v[88:91]
	v_mfma_f32_16x16x32_bf16 v[92:95], v[196:199], v[148:151], v[92:95]
	s_waitcnt vmcnt(0) lgkmcnt(0)
	s_barrier
	s_cmp_ge_u32 s63, 14
	s_cbranch_scc1 .Lg2_ff1_nd16_0
	s_add_u32 s56, s56, 0x80
	s_addc_u32 s57, s57, 0
	s_add_u32 m0, s62, 0x0
	s_add_u32 s4, s56, 0x0
	s_addc_u32 s5, s57, 0
	global_load_lds_dwordx4 v162, s[4:5]
	s_add_u32 m0, s62, 0x1000
	s_add_u32 s4, s56, 0x10000
	s_addc_u32 s5, s57, 0
	global_load_lds_dwordx4 v162, s[4:5]
	s_add_u32 m0, s62, 0x2000
	s_add_u32 s4, s56, 0x20000
	s_addc_u32 s5, s57, 0
	global_load_lds_dwordx4 v162, s[4:5]
	s_add_u32 m0, s62, 0x3000
	s_add_u32 s4, s56, 0x30000
	s_addc_u32 s5, s57, 0
	global_load_lds_dwordx4 v162, s[4:5]
	s_add_u32 m0, s62, 0x4000
	s_add_u32 s4, s56, 0x40000
	s_addc_u32 s5, s57, 0
	global_load_lds_dwordx4 v162, s[4:5]
	s_add_u32 m0, s62, 0x5000
	s_add_u32 s4, s56, 0x50000
	s_addc_u32 s5, s57, 0
	global_load_lds_dwordx4 v162, s[4:5]
	s_add_u32 m0, s62, 0x6000
	s_add_u32 s4, s56, 0x60000
	s_addc_u32 s5, s57, 0
	global_load_lds_dwordx4 v162, s[4:5]
	s_add_u32 m0, s62, 0x7000
	s_add_u32 s4, s56, 0x70000
	s_addc_u32 s5, s57, 0
	global_load_lds_dwordx4 v162, s[4:5]
.Lg2_ff1_nd16_0:
	ds_read_b128 v[136:139], v158 offset:0
	ds_read_b128 v[140:143], v158 offset:2048
	ds_read_b128 v[144:147], v158 offset:4096
	ds_read_b128 v[148:151], v158 offset:6144
	v_mfma_f32_16x16x32_bf16 v[96:99], v[188:191], v[164:167], v[96:99]
	v_mfma_f32_16x16x32_bf16 v[100:103], v[196:199], v[164:167], v[100:103]
	v_mfma_f32_16x16x32_bf16 v[104:107], v[188:191], v[168:171], v[104:107]
	v_mfma_f32_16x16x32_bf16 v[108:111], v[196:199], v[168:171], v[108:111]
	v_mfma_f32_16x16x32_bf16 v[112:115], v[188:191], v[172:175], v[112:115]
	v_mfma_f32_16x16x32_bf16 v[116:119], v[196:199], v[172:175], v[116:119]
	v_mfma_f32_16x16x32_bf16 v[120:123], v[188:191], v[176:179], v[120:123]
	v_mfma_f32_16x16x32_bf16 v[124:127], v[196:199], v[176:179], v[124:127]
	s_cmp_ge_u32 s63, 14
	s_cbranch_scc1 .Lg2_ff1_nb16_1
	s_add_u32 s58, s58, 0x800
	s_addc_u32 s59, s59, 0
	global_load_dwordx4 v[184:187], v160, s[58:59] offset:0
	global_load_dwordx4 v[188:191], v160, s[58:59] offset:1024
	global_load_dwordx4 v[192:195], v161, s[58:59] offset:0
	global_load_dwordx4 v[196:199], v161, s[58:59] offset:1024
.Lg2_ff1_nb16_1:
	ds_read_b128 v[164:167], v158 offset:8192
	ds_read_b128 v[168:171], v158 offset:10240
	ds_read_b128 v[172:175], v158 offset:12288
	ds_read_b128 v[176:179], v158 offset:14336
	s_waitcnt lgkmcnt(4)
	v_mfma_f32_16x16x32_bf16 v[0:3], v[200:203], v[136:139], v[0:3]
	v_mfma_f32_16x16x32_bf16 v[4:7], v[208:211], v[136:139], v[4:7]
	v_mfma_f32_16x16x32_bf16 v[8:11], v[200:203], v[140:143], v[8:11]
	v_mfma_f32_16x16x32_bf16 v[12:15], v[208:211], v[140:143], v[12:15]
	v_mfma_f32_16x16x32_bf16 v[16:19], v[200:203], v[144:147], v[16:19]
	v_mfma_f32_16x16x32_bf16 v[20:23], v[208:211], v[144:147], v[20:23]
	v_mfma_f32_16x16x32_bf16 v[24:27], v[200:203], v[148:151], v[24:27]
	v_mfma_f32_16x16x32_bf16 v[28:31], v[208:211], v[148:151], v[28:31]
	ds_read_b128 v[136:139], v158 offset:16384
	ds_read_b128 v[140:143], v158 offset:18432
	ds_read_b128 v[144:147], v158 offset:20480
	ds_read_b128 v[148:151], v158 offset:22528
	s_waitcnt lgkmcnt(4)
	v_mfma_f32_16x16x32_bf16 v[32:35], v[200:203], v[164:167], v[32:35]
	v_mfma_f32_16x16x32_bf16 v[36:39], v[208:211], v[164:167], v[36:39]
	v_mfma_f32_16x16x32_bf16 v[40:43], v[200:203], v[168:171], v[40:43]
	v_mfma_f32_16x16x32_bf16 v[44:47], v[208:211], v[168:171], v[44:47]
	v_mfma_f32_16x16x32_bf16 v[48:51], v[200:203], v[172:175], v[48:51]
	v_mfma_f32_16x16x32_bf16 v[52:55], v[208:211], v[172:175], v[52:55]
	v_mfma_f32_16x16x32_bf16 v[56:59], v[200:203], v[176:179], v[56:59]
	v_mfma_f32_16x16x32_bf16 v[60:63], v[208:211], v[176:179], v[60:63]
	ds_read_b128 v[164:167], v158 offset:24576
	ds_read_b128 v[168:171], v158 offset:26624
	ds_read_b128 v[172:175], v158 offset:28672
	ds_read_b128 v[176:179], v158 offset:30720
	s_waitcnt lgkmcnt(4)
	v_mfma_f32_16x16x32_bf16 v[64:67], v[200:203], v[136:139], v[64:67]
	v_mfma_f32_16x16x32_bf16 v[68:71], v[208:211], v[136:139], v[68:71]
	v_mfma_f32_16x16x32_bf16 v[72:75], v[200:203], v[140:143], v[72:75]
	v_mfma_f32_16x16x32_bf16 v[76:79], v[208:211], v[140:143], v[76:79]
	v_mfma_f32_16x16x32_bf16 v[80:83], v[200:203], v[144:147], v[80:83]
	v_mfma_f32_16x16x32_bf16 v[84:87], v[208:211], v[144:147], v[84:87]
	v_mfma_f32_16x16x32_bf16 v[88:91], v[200:203], v[148:151], v[88:91]
	v_mfma_f32_16x16x32_bf16 v[92:95], v[208:211], v[148:151], v[92:95]
	ds_read_b128 v[136:139], v159 offset:0
	ds_read_b128 v[140:143], v159 offset:2048
	ds_read_b128 v[144:147], v159 offset:4096
	ds_read_b128 v[148:151], v159 offset:6144
	s_waitcnt lgkmcnt(4)
	v_mfma_f32_16x16x32_bf16 v[96:99], v[200:203], v[164:167], v[96:99]
	v_mfma_f32_16x16x32_bf16 v[100:103], v[208:211], v[164:167], v[100:103]
	v_mfma_f32_16x16x32_bf16 v[104:107], v[200:203], v[168:171], v[104:107]
	v_mfma_f32_16x16x32_bf16 v[108:111], v[208:211], v[168:171], v[108:111]
	v_mfma_f32_16x16x32_bf16 v[112:115], v[200:203], v[172:175], v[112:115]
	v_mfma_f32_16x16x32_bf16 v[116:119], v[208:211], v[172:175], v[116:119]
	v_mfma_f32_16x16x32_bf16 v[120:123], v[200:203], v[176:179], v[120:123]
	v_mfma_f32_16x16x32_bf16 v[124:127], v[208:211], v[176:179], v[124:127]
	ds_read_b128 v[164:167], v159 offset:8192
	ds_read_b128 v[168:171], v159 offset:10240
	ds_read_b128 v[172:175], v159 offset:12288
	ds_read_b128 v[176:179], v159 offset:14336
	s_waitcnt lgkmcnt(4)
	v_mfma_f32_16x16x32_bf16 v[0:3], v[204:207], v[136:139], v[0:3]
	v_mfma_f32_16x16x32_bf16 v[4:7], v[240:243], v[136:139], v[4:7]
	v_mfma_f32_16x16x32_bf16 v[8:11], v[204:207], v[140:143], v[8:11]
	v_mfma_f32_16x16x32_bf16 v[12:15], v[240:243], v[140:143], v[12:15]
	v_mfma_f32_16x16x32_bf16 v[16:19], v[204:207], v[144:147], v[16:19]
	v_mfma_f32_16x16x32_bf16 v[20:23], v[240:243], v[144:147], v[20:23]
	v_mfma_f32_16x16x32_bf16 v[24:27], v[204:207], v[148:151], v[24:27]
	v_mfma_f32_16x16x32_bf16 v[28:31], v[240:243], v[148:151], v[28:31]
	ds_read_b128 v[136:139], v159 offset:16384
	ds_read_b128 v[140:143], v159 offset:18432
	ds_read_b128 v[144:147], v159 offset:20480
	ds_read_b128 v[148:151], v159 offset:22528
	s_waitcnt lgkmcnt(4)
	v_mfma_f32_16x16x32_bf16 v[32:35], v[204:207], v[164:167], v[32:35]
	v_mfma_f32_16x16x32_bf16 v[36:39], v[240:243], v[164:167], v[36:39]
	v_mfma_f32_16x16x32_bf16 v[40:43], v[204:207], v[168:171], v[40:43]
	v_mfma_f32_16x16x32_bf16 v[44:47], v[240:243], v[168:171], v[44:47]
	v_mfma_f32_16x16x32_bf16 v[48:51], v[204:207], v[172:175], v[48:51]
	v_mfma_f32_16x16x32_bf16 v[52:55], v[240:243], v[172:175], v[52:55]
	v_mfma_f32_16x16x32_bf16 v[56:59], v[204:207], v[176:179], v[56:59]
	v_mfma_f32_16x16x32_bf16 v[60:63], v[240:243], v[176:179], v[60:63]
	ds_read_b128 v[164:167], v159 offset:24576
	ds_read_b128 v[168:171], v159 offset:26624
	ds_read_b128 v[172:175], v159 offset:28672
	ds_read_b128 v[176:179], v159 offset:30720
	s_waitcnt lgkmcnt(4)
	v_mfma_f32_16x16x32_bf16 v[64:67], v[204:207], v[136:139], v[64:67]
	v_mfma_f32_16x16x32_bf16 v[68:71], v[240:243], v[136:139], v[68:71]
	v_mfma_f32_16x16x32_bf16 v[72:75], v[204:207], v[140:143], v[72:75]
	v_mfma_f32_16x16x32_bf16 v[76:79], v[240:243], v[140:143], v[76:79]
	v_mfma_f32_16x16x32_bf16 v[80:83], v[204:207], v[144:147], v[80:83]
	v_mfma_f32_16x16x32_bf16 v[84:87], v[240:243], v[144:147], v[84:87]
	v_mfma_f32_16x16x32_bf16 v[88:91], v[204:207], v[148:151], v[88:91]
	v_mfma_f32_16x16x32_bf16 v[92:95], v[240:243], v[148:151], v[92:95]
	s_waitcnt vmcnt(0) lgkmcnt(0)
	s_barrier
	s_cmp_ge_u32 s63, 14
	s_cbranch_scc1 .Lg2_ff1_nd16_1
	s_add_u32 s56, s56, 0x80
	s_addc_u32 s57, s57, 0
	s_add_u32 m0, s62, 0x8800
	s_add_u32 s4, s56, 0x0
	s_addc_u32 s5, s57, 0
	global_load_lds_dwordx4 v162, s[4:5]
	s_add_u32 m0, s62, 0x9800
	s_add_u32 s4, s56, 0x10000
	s_addc_u32 s5, s57, 0
	global_load_lds_dwordx4 v162, s[4:5]
	s_add_u32 m0, s62, 0xa800
	s_add_u32 s4, s56, 0x20000
	s_addc_u32 s5, s57, 0
	global_load_lds_dwordx4 v162, s[4:5]
	s_add_u32 m0, s62, 0xb800
	s_add_u32 s4, s56, 0x30000
	s_addc_u32 s5, s57, 0
	global_load_lds_dwordx4 v162, s[4:5]
	s_add_u32 m0, s62, 0xc800
	s_add_u32 s4, s56, 0x40000
	s_addc_u32 s5, s57, 0
	global_load_lds_dwordx4 v162, s[4:5]
	s_add_u32 m0, s62, 0xd800
	s_add_u32 s4, s56, 0x50000
	s_addc_u32 s5, s57, 0
	global_load_lds_dwordx4 v162, s[4:5]
	s_add_u32 m0, s62, 0xe800
	s_add_u32 s4, s56, 0x60000
	s_addc_u32 s5, s57, 0
	global_load_lds_dwordx4 v162, s[4:5]
	s_add_u32 m0, s62, 0xf800
	s_add_u32 s4, s56, 0x70000
	s_addc_u32 s5, s57, 0
	global_load_lds_dwordx4 v162, s[4:5]
	ds_read_b128 v[136:139], v156 offset:0
	ds_read_b128 v[140:143], v156 offset:2048
	ds_read_b128 v[144:147], v156 offset:4096
	ds_read_b128 v[148:151], v156 offset:6144
.Lg2_ff1_nd16_1:
	v_mfma_f32_16x16x32_bf16 v[96:99], v[204:207], v[164:167], v[96:99]
	v_mfma_f32_16x16x32_bf16 v[100:103], v[240:243], v[164:167], v[100:103]
	v_mfma_f32_16x16x32_bf16 v[104:107], v[204:207], v[168:171], v[104:107]
	v_mfma_f32_16x16x32_bf16 v[108:111], v[240:243], v[168:171], v[108:111]
	v_mfma_f32_16x16x32_bf16 v[112:115], v[204:207], v[172:175], v[112:115]
	v_mfma_f32_16x16x32_bf16 v[116:119], v[240:243], v[172:175], v[116:119]
	v_mfma_f32_16x16x32_bf16 v[120:123], v[204:207], v[176:179], v[120:123]
	v_mfma_f32_16x16x32_bf16 v[124:127], v[240:243], v[176:179], v[124:127]
	s_add_i32 s63, s63, 2
	s_cmp_lt_u32 s63, 16
	s_cbranch_scc1 .Lg2_ff1_loop16
	s_branch .Lg2_ff1_episel

.Lg2_up_nodma_0:
	global_load_dwordx4 v[184:187], v160, s[58:59] offset:0
	global_load_dwordx4 v[188:191], v160, s[58:59] offset:1024
	global_load_dwordx4 v[192:195], v161, s[58:59] offset:0
	global_load_dwordx4 v[196:199], v161, s[58:59] offset:1024
	v_mov_b32_e32 v0, 0
	v_mov_b32_e32 v1, 0
	v_mov_b32_e32 v2, 0
	v_mov_b32_e32 v3, 0
	v_mov_b32_e32 v4, 0
	v_mov_b32_e32 v5, 0
	v_mov_b32_e32 v6, 0
	v_mov_b32_e32 v7, 0
	v_mov_b32_e32 v8, 0
	v_mov_b32_e32 v9, 0
	v_mov_b32_e32 v10, 0
	v_mov_b32_e32 v11, 0
	v_mov_b32_e32 v12, 0
	v_mov_b32_e32 v13, 0
	v_mov_b32_e32 v14, 0
	v_mov_b32_e32 v15, 0
	v_mov_b32_e32 v16, 0
	v_mov_b32_e32 v17, 0
	v_mov_b32_e32 v18, 0
	v_mov_b32_e32 v19, 0
	v_mov_b32_e32 v20, 0
	v_mov_b32_e32 v21, 0
	v_mov_b32_e32 v22, 0
	v_mov_b32_e32 v23, 0
	v_mov_b32_e32 v24, 0
	v_mov_b32_e32 v25, 0
	v_mov_b32_e32 v26, 0
	v_mov_b32_e32 v27, 0
	v_mov_b32_e32 v28, 0
	v_mov_b32_e32 v29, 0
	v_mov_b32_e32 v30, 0
	v_mov_b32_e32 v31, 0
	v_mov_b32_e32 v32, 0
	v_mov_b32_e32 v33, 0
	v_mov_b32_e32 v34, 0
	v_mov_b32_e32 v35, 0
	v_mov_b32_e32 v36, 0
	v_mov_b32_e32 v37, 0
	v_mov_b32_e32 v38, 0
	v_mov_b32_e32 v39, 0
	v_mov_b32_e32 v40, 0
	v_mov_b32_e32 v41, 0
	v_mov_b32_e32 v42, 0
	v_mov_b32_e32 v43, 0
	v_mov_b32_e32 v44, 0
	v_mov_b32_e32 v45, 0
	v_mov_b32_e32 v46, 0
	v_mov_b32_e32 v47, 0
	v_mov_b32_e32 v48, 0
	v_mov_b32_e32 v49, 0
	v_mov_b32_e32 v50, 0
	v_mov_b32_e32 v51, 0
	v_mov_b32_e32 v52, 0
	v_mov_b32_e32 v53, 0
	v_mov_b32_e32 v54, 0
	v_mov_b32_e32 v55, 0
	v_mov_b32_e32 v56, 0
	v_mov_b32_e32 v57, 0
	v_mov_b32_e32 v58, 0
	v_mov_b32_e32 v59, 0
	v_mov_b32_e32 v60, 0
	v_mov_b32_e32 v61, 0
	v_mov_b32_e32 v62, 0
	v_mov_b32_e32 v63, 0
	v_mov_b32_e32 v64, 0
	v_mov_b32_e32 v65, 0
	v_mov_b32_e32 v66, 0
	v_mov_b32_e32 v67, 0
	v_mov_b32_e32 v68, 0
	v_mov_b32_e32 v69, 0
	v_mov_b32_e32 v70, 0
	v_mov_b32_e32 v71, 0
	v_mov_b32_e32 v72, 0
	v_mov_b32_e32 v73, 0
	v_mov_b32_e32 v74, 0
	v_mov_b32_e32 v75, 0
	v_mov_b32_e32 v76, 0
	v_mov_b32_e32 v77, 0
	v_mov_b32_e32 v78, 0
	v_mov_b32_e32 v79, 0
	v_mov_b32_e32 v80, 0
	v_mov_b32_e32 v81, 0
	v_mov_b32_e32 v82, 0
	v_mov_b32_e32 v83, 0
	v_mov_b32_e32 v84, 0
	v_mov_b32_e32 v85, 0
	v_mov_b32_e32 v86, 0
	v_mov_b32_e32 v87, 0
	v_mov_b32_e32 v88, 0
	v_mov_b32_e32 v89, 0
	v_mov_b32_e32 v90, 0
	v_mov_b32_e32 v91, 0
	v_mov_b32_e32 v92, 0
	v_mov_b32_e32 v93, 0
	v_mov_b32_e32 v94, 0
	v_mov_b32_e32 v95, 0
	v_mov_b32_e32 v96, 0
	v_mov_b32_e32 v97, 0
	v_mov_b32_e32 v98, 0
	v_mov_b32_e32 v99, 0
	v_mov_b32_e32 v100, 0
	v_mov_b32_e32 v101, 0
	v_mov_b32_e32 v102, 0
	v_mov_b32_e32 v103, 0
	v_mov_b32_e32 v104, 0
	v_mov_b32_e32 v105, 0
	v_mov_b32_e32 v106, 0
	v_mov_b32_e32 v107, 0
	v_mov_b32_e32 v108, 0
	v_mov_b32_e32 v109, 0
	v_mov_b32_e32 v110, 0
	v_mov_b32_e32 v111, 0
	v_mov_b32_e32 v112, 0
	v_mov_b32_e32 v113, 0
	v_mov_b32_e32 v114, 0
	v_mov_b32_e32 v115, 0
	v_mov_b32_e32 v116, 0
	v_mov_b32_e32 v117, 0
	v_mov_b32_e32 v118, 0
	v_mov_b32_e32 v119, 0
	v_mov_b32_e32 v120, 0
	v_mov_b32_e32 v121, 0
	v_mov_b32_e32 v122, 0
	v_mov_b32_e32 v123, 0
	v_mov_b32_e32 v124, 0
	v_mov_b32_e32 v125, 0
	v_mov_b32_e32 v126, 0
	v_mov_b32_e32 v127, 0
	v_mov_b32_e32 v128, 0
	v_mov_b32_e32 v129, 0
	v_mov_b32_e32 v130, 0
	v_mov_b32_e32 v131, 0
	v_mov_b32_e32 v132, 0
	v_mov_b32_e32 v133, 0
	v_mov_b32_e32 v134, 0
	v_mov_b32_e32 v135, 0
	s_mov_b32 s63, 0
	s_waitcnt vmcnt(0)
	s_barrier
	s_add_u32 s56, s56, 0x80
	s_addc_u32 s57, s57, 0
	s_add_u32 m0, s62, 0x8800
	s_add_u32 s4, s56, 0x0
	s_addc_u32 s5, s57, 0
	global_load_lds_dwordx4 v162, s[4:5]
	s_add_u32 m0, s62, 0x9800
	s_add_u32 s4, s56, 0x72000
	s_addc_u32 s5, s57, 0
	global_load_lds_dwordx4 v162, s[4:5]
	s_add_u32 m0, s62, 0xa800
	s_add_u32 s4, s56, 0xe4000
	s_addc_u32 s5, s57, 0
	global_load_lds_dwordx4 v162, s[4:5]
	s_add_u32 m0, s62, 0xb800
	s_add_u32 s4, s56, 0x156000
	s_addc_u32 s5, s57, 0
	global_load_lds_dwordx4 v162, s[4:5]
	s_add_u32 m0, s62, 0xc800
	s_add_u32 s4, s56, 0x1c8000
	s_addc_u32 s5, s57, 0
	global_load_lds_dwordx4 v162, s[4:5]
	s_add_u32 m0, s62, 0xd800
	s_add_u32 s4, s56, 0x23a000
	s_addc_u32 s5, s57, 0
	global_load_lds_dwordx4 v162, s[4:5]
	s_add_u32 m0, s62, 0xe800
	s_add_u32 s4, s56, 0x2ac000
	s_addc_u32 s5, s57, 0
	global_load_lds_dwordx4 v162, s[4:5]
	s_add_u32 m0, s62, 0xf800
	s_add_u32 s4, s56, 0x31e000
	s_addc_u32 s5, s57, 0
	global_load_lds_dwordx4 v162, s[4:5]
	s_cmp_gt_u32 s70, 1
	s_cbranch_scc1 .Lg2_up_nodma_1
	s_add_u32 m0, s62, 0x10800
	s_add_u32 s4, s56, 0x390000
	s_addc_u32 s5, s57, 0
	global_load_lds_dwordx4 v162, s[4:5]

.Lg2_up_loop17:
	s_add_u32 s58, s58, 0x800
	s_addc_u32 s59, s59, 0
	global_load_dwordx4 v[200:203], v160, s[58:59] offset:0
	global_load_dwordx4 v[204:207], v160, s[58:59] offset:1024
	global_load_dwordx4 v[208:211], v161, s[58:59] offset:0
	global_load_dwordx4 v[240:243], v161, s[58:59] offset:1024
	ds_read_b128 v[164:167], v156 offset:8192
	ds_read_b128 v[168:171], v156 offset:10240
	ds_read_b128 v[172:175], v156 offset:12288
	ds_read_b128 v[176:179], v156 offset:14336
	s_waitcnt lgkmcnt(4)
	v_mfma_f32_16x16x32_bf16 v[0:3], v[184:187], v[136:139], v[0:3]
	v_mfma_f32_16x16x32_bf16 v[4:7], v[192:195], v[136:139], v[4:7]
	v_mfma_f32_16x16x32_bf16 v[8:11], v[184:187], v[140:143], v[8:11]
	v_mfma_f32_16x16x32_bf16 v[12:15], v[192:195], v[140:143], v[12:15]
	v_mfma_f32_16x16x32_bf16 v[16:19], v[184:187], v[144:147], v[16:19]
	v_mfma_f32_16x16x32_bf16 v[20:23], v[192:195], v[144:147], v[20:23]
	v_mfma_f32_16x16x32_bf16 v[24:27], v[184:187], v[148:151], v[24:27]
	v_mfma_f32_16x16x32_bf16 v[28:31], v[192:195], v[148:151], v[28:31]
	ds_read_b128 v[136:139], v156 offset:16384
	ds_read_b128 v[140:143], v156 offset:18432
	ds_read_b128 v[144:147], v156 offset:20480
	ds_read_b128 v[148:151], v156 offset:22528
	s_waitcnt lgkmcnt(4)
	v_mfma_f32_16x16x32_bf16 v[32:35], v[184:187], v[164:167], v[32:35]
	v_mfma_f32_16x16x32_bf16 v[36:39], v[192:195], v[164:167], v[36:39]
	v_mfma_f32_16x16x32_bf16 v[40:43], v[184:187], v[168:171], v[40:43]
	v_mfma_f32_16x16x32_bf16 v[44:47], v[192:195], v[168:171], v[44:47]
	v_mfma_f32_16x16x32_bf16 v[48:51], v[184:187], v[172:175], v[48:51]
	v_mfma_f32_16x16x32_bf16 v[52:55], v[192:195], v[172:175], v[52:55]
	v_mfma_f32_16x16x32_bf16 v[56:59], v[184:187], v[176:179], v[56:59]
	v_mfma_f32_16x16x32_bf16 v[60:63], v[192:195], v[176:179], v[60:63]
	ds_read_b128 v[164:167], v156 offset:24576
	ds_read_b128 v[168:171], v156 offset:26624
	ds_read_b128 v[172:175], v156 offset:28672
	ds_read_b128 v[176:179], v156 offset:30720
	ds_read_b128 v[180:183], v156 offset:32768
	s_waitcnt lgkmcnt(5)
	v_mfma_f32_16x16x32_bf16 v[64:67], v[184:187], v[136:139], v[64:67]
	v_mfma_f32_16x16x32_bf16 v[68:71], v[192:195], v[136:139], v[68:71]
	v_mfma_f32_16x16x32_bf16 v[72:75], v[184:187], v[140:143], v[72:75]
	v_mfma_f32_16x16x32_bf16 v[76:79], v[192:195], v[140:143], v[76:79]
	v_mfma_f32_16x16x32_bf16 v[80:83], v[184:187], v[144:147], v[80:83]
	v_mfma_f32_16x16x32_bf16 v[84:87], v[192:195], v[144:147], v[84:87]
	v_mfma_f32_16x16x32_bf16 v[88:91], v[184:187], v[148:151], v[88:91]
	v_mfma_f32_16x16x32_bf16 v[92:95], v[192:195], v[148:151], v[92:95]
	ds_read_b128 v[136:139], v157 offset:0
	ds_read_b128 v[140:143], v157 offset:2048
	ds_read_b128 v[144:147], v157 offset:4096
	ds_read_b128 v[148:151], v157 offset:6144
	s_waitcnt lgkmcnt(4)
	v_mfma_f32_16x16x32_bf16 v[96:99], v[184:187], v[164:167], v[96:99]
	v_mfma_f32_16x16x32_bf16 v[100:103], v[192:195], v[164:167], v[100:103]
	v_mfma_f32_16x16x32_bf16 v[104:107], v[184:187], v[168:171], v[104:107]
	v_mfma_f32_16x16x32_bf16 v[108:111], v[192:195], v[168:171], v[108:111]
	v_mfma_f32_16x16x32_bf16 v[112:115], v[184:187], v[172:175], v[112:115]
	v_mfma_f32_16x16x32_bf16 v[116:119], v[192:195], v[172:175], v[116:119]
	v_mfma_f32_16x16x32_bf16 v[120:123], v[184:187], v[176:179], v[120:123]
	v_mfma_f32_16x16x32_bf16 v[124:127], v[192:195], v[176:179], v[124:127]
	v_mfma_f32_16x16x32_bf16 v[128:131], v[184:187], v[180:183], v[128:131]
	v_mfma_f32_16x16x32_bf16 v[132:135], v[192:195], v[180:183], v[132:135]
	ds_read_b128 v[164:167], v157 offset:8192
	ds_read_b128 v[168:171], v157 offset:10240
	ds_read_b128 v[172:175], v157 offset:12288
	ds_read_b128 v[176:179], v157 offset:14336
	s_waitcnt lgkmcnt(4)
	v_mfma_f32_16x16x32_bf16 v[0:3], v[188:191], v[136:139], v[0:3]
	v_mfma_f32_16x16x32_bf16 v[4:7], v[196:199], v[136:139], v[4:7]
	v_mfma_f32_16x16x32_bf16 v[8:11], v[188:191], v[140:143], v[8:11]
	v_mfma_f32_16x16x32_bf16 v[12:15], v[196:199], v[140:143], v[12:15]
	v_mfma_f32_16x16x32_bf16 v[16:19], v[188:191], v[144:147], v[16:19]
	v_mfma_f32_16x16x32_bf16 v[20:23], v[196:199], v[144:147], v[20:23]
	v_mfma_f32_16x16x32_bf16 v[24:27], v[188:191], v[148:151], v[24:27]
	v_mfma_f32_16x16x32_bf16 v[28:31], v[196:199], v[148:151], v[28:31]
	ds_read_b128 v[136:139], v157 offset:16384
	ds_read_b128 v[140:143], v157 offset:18432
	ds_read_b128 v[144:147], v157 offset:20480
	ds_read_b128 v[148:151], v157 offset:22528
	s_waitcnt lgkmcnt(4)
	v_mfma_f32_16x16x32_bf16 v[32:35], v[188:191], v[164:167], v[32:35]
	v_mfma_f32_16x16x32_bf16 v[36:39], v[196:199], v[164:167], v[36:39]
	v_mfma_f32_16x16x32_bf16 v[40:43], v[188:191], v[168:171], v[40:43]
	v_mfma_f32_16x16x32_bf16 v[44:47], v[196:199], v[168:171], v[44:47]
	v_mfma_f32_16x16x32_bf16 v[48:51], v[188:191], v[172:175], v[48:51]
	v_mfma_f32_16x16x32_bf16 v[52:55], v[196:199], v[172:175], v[52:55]
	v_mfma_f32_16x16x32_bf16 v[56:59], v[188:191], v[176:179], v[56:59]
	v_mfma_f32_16x16x32_bf16 v[60:63], v[196:199], v[176:179], v[60:63]
	ds_read_b128 v[164:167], v157 offset:24576
	ds_read_b128 v[168:171], v157 offset:26624
	ds_read_b128 v[172:175], v157 offset:28672
	ds_read_b128 v[176:179], v157 offset:30720
	ds_read_b128 v[180:183], v157 offset:32768
	s_waitcnt lgkmcnt(5)
	v_mfma_f32_16x16x32_bf16 v[64:67], v[188:191], v[136:139], v[64:67]
	v_mfma_f32_16x16x32_bf16 v[68:71], v[196:199], v[136:139], v[68:71]
	v_mfma_f32_16x16x32_bf16 v[72:75], v[188:191], v[140:143], v[72:75]
	v_mfma_f32_16x16x32_bf16 v[76:79], v[196:199], v[140:143], v[76:79]
	v_mfma_f32_16x16x32_bf16 v[80:83], v[188:191], v[144:147], v[80:83]
	v_mfma_f32_16x16x32_bf16 v[84:87], v[196:199], v[144:147], v[84:87]
	v_mfma_f32_16x16x32_bf16 v[88:91], v[188:191], v[148:151], v[88:91]
	v_mfma_f32_16x16x32_bf16 v[92:95], v[196:199], v[148:151], v[92:95]
	s_waitcnt vmcnt(0) lgkmcnt(0)
	s_barrier
	s_cmp_ge_u32 s63, 2
	s_cbranch_scc1 .Lg2_up_nd17_0
	s_add_u32 s56, s56, 0x80
	s_addc_u32 s57, s57, 0
	s_add_u32 m0, s62, 0x0
	s_add_u32 s4, s56, 0x0
	s_addc_u32 s5, s57, 0
	global_load_lds_dwordx4 v162, s[4:5]
	s_add_u32 m0, s62, 0x1000
	s_add_u32 s4, s56, 0x72000
	s_addc_u32 s5, s57, 0
	global_load_lds_dwordx4 v162, s[4:5]
	s_add_u32 m0, s62, 0x2000
	s_add_u32 s4, s56, 0xe4000
	s_addc_u32 s5, s57, 0
	global_load_lds_dwordx4 v162, s[4:5]
	s_add_u32 m0, s62, 0x3000
	s_add_u32 s4, s56, 0x156000
	s_addc_u32 s5, s57, 0
	global_load_lds_dwordx4 v162, s[4:5]
	s_add_u32 m0, s62, 0x4000
	s_add_u32 s4, s56, 0x1c8000
	s_addc_u32 s5, s57, 0
	global_load_lds_dwordx4 v162, s[4:5]
	s_add_u32 m0, s62, 0x5000
	s_add_u32 s4, s56, 0x23a000
	s_addc_u32 s5, s57, 0
	global_load_lds_dwordx4 v162, s[4:5]
	s_add_u32 m0, s62, 0x6000
	s_add_u32 s4, s56, 0x2ac000
	s_addc_u32 s5, s57, 0
	global_load_lds_dwordx4 v162, s[4:5]
	s_add_u32 m0, s62, 0x7000
	s_add_u32 s4, s56, 0x31e000
	s_addc_u32 s5, s57, 0
	global_load_lds_dwordx4 v162, s[4:5]
	s_cmp_gt_u32 s70, 1
	s_cbranch_scc1 .Lg2_up_nodma_2
	s_add_u32 m0, s62, 0x8000
	s_add_u32 s4, s56, 0x390000
	s_addc_u32 s5, s57, 0
	global_load_lds_dwordx4 v162, s[4:5]
.Lg2_up_nodma_2:
.Lg2_up_nd17_0:
	ds_read_b128 v[136:139], v158 offset:0
	ds_read_b128 v[140:143], v158 offset:2048
	ds_read_b128 v[144:147], v158 offset:4096
	ds_read_b128 v[148:151], v158 offset:6144
	v_mfma_f32_16x16x32_bf16 v[96:99], v[188:191], v[164:167], v[96:99]
	v_mfma_f32_16x16x32_bf16 v[100:103], v[196:199], v[164:167], v[100:103]
	v_mfma_f32_16x16x32_bf16 v[104:107], v[188:191], v[168:171], v[104:107]
	v_mfma_f32_16x16x32_bf16 v[108:111], v[196:199], v[168:171], v[108:111]
	v_mfma_f32_16x16x32_bf16 v[112:115], v[188:191], v[172:175], v[112:115]
	v_mfma_f32_16x16x32_bf16 v[116:119], v[196:199], v[172:175], v[116:119]
	v_mfma_f32_16x16x32_bf16 v[120:123], v[188:191], v[176:179], v[120:123]
	v_mfma_f32_16x16x32_bf16 v[124:127], v[196:199], v[176:179], v[124:127]
	v_mfma_f32_16x16x32_bf16 v[128:131], v[188:191], v[180:183], v[128:131]
	v_mfma_f32_16x16x32_bf16 v[132:135], v[196:199], v[180:183], v[132:135]
	s_cmp_ge_u32 s63, 2
	s_cbranch_scc1 .Lg2_up_nb17_1
	s_add_u32 s58, s58, 0x800
	s_addc_u32 s59, s59, 0
	global_load_dwordx4 v[184:187], v160, s[58:59] offset:0
	global_load_dwordx4 v[188:191], v160, s[58:59] offset:1024
	global_load_dwordx4 v[192:195], v161, s[58:59] offset:0
	global_load_dwordx4 v[196:199], v161, s[58:59] offset:1024
.Lg2_up_nb17_1:
	ds_read_b128 v[164:167], v158 offset:8192
	ds_read_b128 v[168:171], v158 offset:10240
	ds_read_b128 v[172:175], v158 offset:12288
	ds_read_b128 v[176:179], v158 offset:14336
	s_waitcnt lgkmcnt(4)
	v_mfma_f32_16x16x32_bf16 v[0:3], v[200:203], v[136:139], v[0:3]
	v_mfma_f32_16x16x32_bf16 v[4:7], v[208:211], v[136:139], v[4:7]
	v_mfma_f32_16x16x32_bf16 v[8:11], v[200:203], v[140:143], v[8:11]
	v_mfma_f32_16x16x32_bf16 v[12:15], v[208:211], v[140:143], v[12:15]
	v_mfma_f32_16x16x32_bf16 v[16:19], v[200:203], v[144:147], v[16:19]
	v_mfma_f32_16x16x32_bf16 v[20:23], v[208:211], v[144:147], v[20:23]
	v_mfma_f32_16x16x32_bf16 v[24:27], v[200:203], v[148:151], v[24:27]
	v_mfma_f32_16x16x32_bf16 v[28:31], v[208:211], v[148:151], v[28:31]
	ds_read_b128 v[136:139], v158 offset:16384
	ds_read_b128 v[140:143], v158 offset:18432
	ds_read_b128 v[144:147], v158 offset:20480
	ds_read_b128 v[148:151], v158 offset:22528
	s_waitcnt lgkmcnt(4)
	v_mfma_f32_16x16x32_bf16 v[32:35], v[200:203], v[164:167], v[32:35]
	v_mfma_f32_16x16x32_bf16 v[36:39], v[208:211], v[164:167], v[36:39]
	v_mfma_f32_16x16x32_bf16 v[40:43], v[200:203], v[168:171], v[40:43]
	v_mfma_f32_16x16x32_bf16 v[44:47], v[208:211], v[168:171], v[44:47]
	v_mfma_f32_16x16x32_bf16 v[48:51], v[200:203], v[172:175], v[48:51]
	v_mfma_f32_16x16x32_bf16 v[52:55], v[208:211], v[172:175], v[52:55]
	v_mfma_f32_16x16x32_bf16 v[56:59], v[200:203], v[176:179], v[56:59]
	v_mfma_f32_16x16x32_bf16 v[60:63], v[208:211], v[176:179], v[60:63]
	ds_read_b128 v[164:167], v158 offset:24576
	ds_read_b128 v[168:171], v158 offset:26624
	ds_read_b128 v[172:175], v158 offset:28672
	ds_read_b128 v[176:179], v158 offset:30720
	ds_read_b128 v[180:183], v158 offset:32768
	s_waitcnt lgkmcnt(5)
	v_mfma_f32_16x16x32_bf16 v[64:67], v[200:203], v[136:139], v[64:67]
	v_mfma_f32_16x16x32_bf16 v[68:71], v[208:211], v[136:139], v[68:71]
	v_mfma_f32_16x16x32_bf16 v[72:75], v[200:203], v[140:143], v[72:75]
	v_mfma_f32_16x16x32_bf16 v[76:79], v[208:211], v[140:143], v[76:79]
	v_mfma_f32_16x16x32_bf16 v[80:83], v[200:203], v[144:147], v[80:83]
	v_mfma_f32_16x16x32_bf16 v[84:87], v[208:211], v[144:147], v[84:87]
	v_mfma_f32_16x16x32_bf16 v[88:91], v[200:203], v[148:151], v[88:91]
	v_mfma_f32_16x16x32_bf16 v[92:95], v[208:211], v[148:151], v[92:95]
	ds_read_b128 v[136:139], v159 offset:0
	ds_read_b128 v[140:143], v159 offset:2048
	ds_read_b128 v[144:147], v159 offset:4096
	ds_read_b128 v[148:151], v159 offset:6144
	s_waitcnt lgkmcnt(4)
	v_mfma_f32_16x16x32_bf16 v[96:99], v[200:203], v[164:167], v[96:99]
	v_mfma_f32_16x16x32_bf16 v[100:103], v[208:211], v[164:167], v[100:103]
	v_mfma_f32_16x16x32_bf16 v[104:107], v[200:203], v[168:171], v[104:107]
	v_mfma_f32_16x16x32_bf16 v[108:111], v[208:211], v[168:171], v[108:111]
	v_mfma_f32_16x16x32_bf16 v[112:115], v[200:203], v[172:175], v[112:115]
	v_mfma_f32_16x16x32_bf16 v[116:119], v[208:211], v[172:175], v[116:119]
	v_mfma_f32_16x16x32_bf16 v[120:123], v[200:203], v[176:179], v[120:123]
	v_mfma_f32_16x16x32_bf16 v[124:127], v[208:211], v[176:179], v[124:127]
	v_mfma_f32_16x16x32_bf16 v[128:131], v[200:203], v[180:183], v[128:131]
	v_mfma_f32_16x16x32_bf16 v[132:135], v[208:211], v[180:183], v[132:135]
	ds_read_b128 v[164:167], v159 offset:8192
	ds_read_b128 v[168:171], v159 offset:10240
	ds_read_b128 v[172:175], v159 offset:12288
	ds_read_b128 v[176:179], v159 offset:14336
	s_waitcnt lgkmcnt(4)
	v_mfma_f32_16x16x32_bf16 v[0:3], v[204:207], v[136:139], v[0:3]
	v_mfma_f32_16x16x32_bf16 v[4:7], v[240:243], v[136:139], v[4:7]
	v_mfma_f32_16x16x32_bf16 v[8:11], v[204:207], v[140:143], v[8:11]
	v_mfma_f32_16x16x32_bf16 v[12:15], v[240:243], v[140:143], v[12:15]
	v_mfma_f32_16x16x32_bf16 v[16:19], v[204:207], v[144:147], v[16:19]
	v_mfma_f32_16x16x32_bf16 v[20:23], v[240:243], v[144:147], v[20:23]
	v_mfma_f32_16x16x32_bf16 v[24:27], v[204:207], v[148:151], v[24:27]
	v_mfma_f32_16x16x32_bf16 v[28:31], v[240:243], v[148:151], v[28:31]
	ds_read_b128 v[136:139], v159 offset:16384
	ds_read_b128 v[140:143], v159 offset:18432
	ds_read_b128 v[144:147], v159 offset:20480
	ds_read_b128 v[148:151], v159 offset:22528
	s_waitcnt lgkmcnt(4)
	v_mfma_f32_16x16x32_bf16 v[32:35], v[204:207], v[164:167], v[32:35]
	v_mfma_f32_16x16x32_bf16 v[36:39], v[240:243], v[164:167], v[36:39]
	v_mfma_f32_16x16x32_bf16 v[40:43], v[204:207], v[168:171], v[40:43]
	v_mfma_f32_16x16x32_bf16 v[44:47], v[240:243], v[168:171], v[44:47]
	v_mfma_f32_16x16x32_bf16 v[48:51], v[204:207], v[172:175], v[48:51]
	v_mfma_f32_16x16x32_bf16 v[52:55], v[240:243], v[172:175], v[52:55]
	v_mfma_f32_16x16x32_bf16 v[56:59], v[204:207], v[176:179], v[56:59]
	v_mfma_f32_16x16x32_bf16 v[60:63], v[240:243], v[176:179], v[60:63]
	ds_read_b128 v[164:167], v159 offset:24576
	ds_read_b128 v[168:171], v159 offset:26624
	ds_read_b128 v[172:175], v159 offset:28672
	ds_read_b128 v[176:179], v159 offset:30720
	ds_read_b128 v[180:183], v159 offset:32768
	s_waitcnt lgkmcnt(5)
	v_mfma_f32_16x16x32_bf16 v[64:67], v[204:207], v[136:139], v[64:67]
	v_mfma_f32_16x16x32_bf16 v[68:71], v[240:243], v[136:139], v[68:71]
	v_mfma_f32_16x16x32_bf16 v[72:75], v[204:207], v[140:143], v[72:75]
	v_mfma_f32_16x16x32_bf16 v[76:79], v[240:243], v[140:143], v[76:79]
	v_mfma_f32_16x16x32_bf16 v[80:83], v[204:207], v[144:147], v[80:83]
	v_mfma_f32_16x16x32_bf16 v[84:87], v[240:243], v[144:147], v[84:87]
	v_mfma_f32_16x16x32_bf16 v[88:91], v[204:207], v[148:151], v[88:91]
	v_mfma_f32_16x16x32_bf16 v[92:95], v[240:243], v[148:151], v[92:95]
	s_waitcnt vmcnt(0) lgkmcnt(0)
	s_barrier
	s_cmp_ge_u32 s63, 2
	s_cbranch_scc1 .Lg2_up_nd17_1
	s_add_u32 s56, s56, 0x80
	s_addc_u32 s57, s57, 0
	s_add_u32 m0, s62, 0x8800
	s_add_u32 s4, s56, 0x0
	s_addc_u32 s5, s57, 0
	global_load_lds_dwordx4 v162, s[4:5]
	s_add_u32 m0, s62, 0x9800
	s_add_u32 s4, s56, 0x72000
	s_addc_u32 s5, s57, 0
	global_load_lds_dwordx4 v162, s[4:5]
	s_add_u32 m0, s62, 0xa800
	s_add_u32 s4, s56, 0xe4000
	s_addc_u32 s5, s57, 0
	global_load_lds_dwordx4 v162, s[4:5]
	s_add_u32 m0, s62, 0xb800
	s_add_u32 s4, s56, 0x156000
	s_addc_u32 s5, s57, 0
	global_load_lds_dwordx4 v162, s[4:5]
	s_add_u32 m0, s62, 0xc800
	s_add_u32 s4, s56, 0x1c8000
	s_addc_u32 s5, s57, 0
	global_load_lds_dwordx4 v162, s[4:5]
	s_add_u32 m0, s62, 0xd800
	s_add_u32 s4, s56, 0x23a000
	s_addc_u32 s5, s57, 0
	global_load_lds_dwordx4 v162, s[4:5]
	s_add_u32 m0, s62, 0xe800
	s_add_u32 s4, s56, 0x2ac000
	s_addc_u32 s5, s57, 0
	global_load_lds_dwordx4 v162, s[4:5]
	s_add_u32 m0, s62, 0xf800
	s_add_u32 s4, s56, 0x31e000
	s_addc_u32 s5, s57, 0
	global_load_lds_dwordx4 v162, s[4:5]
	s_cmp_gt_u32 s70, 1
	s_cbranch_scc1 .Lg2_up_nodma_3
	s_add_u32 m0, s62, 0x10800
	s_add_u32 s4, s56, 0x390000
	s_addc_u32 s5, s57, 0
	global_load_lds_dwordx4 v162, s[4:5]

.Lg2_up_nd17_1:
	v_mfma_f32_16x16x32_bf16 v[96:99], v[204:207], v[164:167], v[96:99]
	v_mfma_f32_16x16x32_bf16 v[100:103], v[240:243], v[164:167], v[100:103]
	v_mfma_f32_16x16x32_bf16 v[104:107], v[204:207], v[168:171], v[104:107]
	v_mfma_f32_16x16x32_bf16 v[108:111], v[240:243], v[168:171], v[108:111]
	v_mfma_f32_16x16x32_bf16 v[112:115], v[204:207], v[172:175], v[112:115]
	v_mfma_f32_16x16x32_bf16 v[116:119], v[240:243], v[172:175], v[116:119]
	v_mfma_f32_16x16x32_bf16 v[120:123], v[204:207], v[176:179], v[120:123]
	v_mfma_f32_16x16x32_bf16 v[124:127], v[240:243], v[176:179], v[124:127]
	v_mfma_f32_16x16x32_bf16 v[128:131], v[204:207], v[180:183], v[128:131]
	v_mfma_f32_16x16x32_bf16 v[132:135], v[240:243], v[180:183], v[132:135]
	s_add_i32 s63, s63, 2
	s_cmp_lt_u32 s63, 4
	s_cbranch_scc1 .Lg2_up_loop17
	s_branch .Lg2_up_episel
.Lg2_up_k16:
	s_add_u32 m0, s62, 0x0
	s_add_u32 s4, s56, 0x0
	s_addc_u32 s5, s57, 0
	global_load_lds_dwordx4 v162, s[4:5]
	s_add_u32 m0, s62, 0x1000
	s_add_u32 s4, s56, 0x72000
	s_addc_u32 s5, s57, 0
	global_load_lds_dwordx4 v162, s[4:5]
	s_add_u32 m0, s62, 0x2000
	s_add_u32 s4, s56, 0xe4000
	s_addc_u32 s5, s57, 0
	global_load_lds_dwordx4 v162, s[4:5]
	s_add_u32 m0, s62, 0x3000
	s_add_u32 s4, s56, 0x156000
	s_addc_u32 s5, s57, 0
	global_load_lds_dwordx4 v162, s[4:5]
	s_add_u32 m0, s62, 0x4000
	s_add_u32 s4, s56, 0x1c8000
	s_addc_u32 s5, s57, 0
	global_load_lds_dwordx4 v162, s[4:5]
	s_add_u32 m0, s62, 0x5000
	s_add_u32 s4, s56, 0x23a000
	s_addc_u32 s5, s57, 0
	global_load_lds_dwordx4 v162, s[4:5]
	s_add_u32 m0, s62, 0x6000
	s_add_u32 s4, s56, 0x2ac000
	s_addc_u32 s5, s57, 0
	global_load_lds_dwordx4 v162, s[4:5]
	s_add_u32 m0, s62, 0x7000
	s_add_u32 s4, s56, 0x31e000
	s_addc_u32 s5, s57, 0
	global_load_lds_dwordx4 v162, s[4:5]
	global_load_dwordx4 v[184:187], v160, s[58:59] offset:0
	global_load_dwordx4 v[188:191], v160, s[58:59] offset:1024
	global_load_dwordx4 v[192:195], v161, s[58:59] offset:0
	global_load_dwordx4 v[196:199], v161, s[58:59] offset:1024
	v_mov_b32_e32 v0, 0
	v_mov_b32_e32 v1, 0
	v_mov_b32_e32 v2, 0
	v_mov_b32_e32 v3, 0
	v_mov_b32_e32 v4, 0
	v_mov_b32_e32 v5, 0
	v_mov_b32_e32 v6, 0
	v_mov_b32_e32 v7, 0
	v_mov_b32_e32 v8, 0
	v_mov_b32_e32 v9, 0
	v_mov_b32_e32 v10, 0
	v_mov_b32_e32 v11, 0
	v_mov_b32_e32 v12, 0
	v_mov_b32_e32 v13, 0
	v_mov_b32_e32 v14, 0
	v_mov_b32_e32 v15, 0
	v_mov_b32_e32 v16, 0
	v_mov_b32_e32 v17, 0
	v_mov_b32_e32 v18, 0
	v_mov_b32_e32 v19, 0
	v_mov_b32_e32 v20, 0
	v_mov_b32_e32 v21, 0
	v_mov_b32_e32 v22, 0
	v_mov_b32_e32 v23, 0
	v_mov_b32_e32 v24, 0
	v_mov_b32_e32 v25, 0
	v_mov_b32_e32 v26, 0
	v_mov_b32_e32 v27, 0
	v_mov_b32_e32 v28, 0
	v_mov_b32_e32 v29, 0
	v_mov_b32_e32 v30, 0
	v_mov_b32_e32 v31, 0
	v_mov_b32_e32 v32, 0
	v_mov_b32_e32 v33, 0
	v_mov_b32_e32 v34, 0
	v_mov_b32_e32 v35, 0
	v_mov_b32_e32 v36, 0
	v_mov_b32_e32 v37, 0
	v_mov_b32_e32 v38, 0
	v_mov_b32_e32 v39, 0
	v_mov_b32_e32 v40, 0
	v_mov_b32_e32 v41, 0
	v_mov_b32_e32 v42, 0
	v_mov_b32_e32 v43, 0
	v_mov_b32_e32 v44, 0
	v_mov_b32_e32 v45, 0
	v_mov_b32_e32 v46, 0
	v_mov_b32_e32 v47, 0
	v_mov_b32_e32 v48, 0
	v_mov_b32_e32 v49, 0
	v_mov_b32_e32 v50, 0
	v_mov_b32_e32 v51, 0
	v_mov_b32_e32 v52, 0
	v_mov_b32_e32 v53, 0
	v_mov_b32_e32 v54, 0
	v_mov_b32_e32 v55, 0
	v_mov_b32_e32 v56, 0
	v_mov_b32_e32 v57, 0
	v_mov_b32_e32 v58, 0
	v_mov_b32_e32 v59, 0
	v_mov_b32_e32 v60, 0
	v_mov_b32_e32 v61, 0
	v_mov_b32_e32 v62, 0
	v_mov_b32_e32 v63, 0
	v_mov_b32_e32 v64, 0
	v_mov_b32_e32 v65, 0
	v_mov_b32_e32 v66, 0
	v_mov_b32_e32 v67, 0
	v_mov_b32_e32 v68, 0
	v_mov_b32_e32 v69, 0
	v_mov_b32_e32 v70, 0
	v_mov_b32_e32 v71, 0
	v_mov_b32_e32 v72, 0
	v_mov_b32_e32 v73, 0
	v_mov_b32_e32 v74, 0
	v_mov_b32_e32 v75, 0
	v_mov_b32_e32 v76, 0
	v_mov_b32_e32 v77, 0
	v_mov_b32_e32 v78, 0
	v_mov_b32_e32 v79, 0
	v_mov_b32_e32 v80, 0
	v_mov_b32_e32 v81, 0
	v_mov_b32_e32 v82, 0
	v_mov_b32_e32 v83, 0
	v_mov_b32_e32 v84, 0
	v_mov_b32_e32 v85, 0
	v_mov_b32_e32 v86, 0
	v_mov_b32_e32 v87, 0
	v_mov_b32_e32 v88, 0
	v_mov_b32_e32 v89, 0
	v_mov_b32_e32 v90, 0
	v_mov_b32_e32 v91, 0
	v_mov_b32_e32 v92, 0
	v_mov_b32_e32 v93, 0
	v_mov_b32_e32 v94, 0
	v_mov_b32_e32 v95, 0
	v_mov_b32_e32 v96, 0
	v_mov_b32_e32 v97, 0
	v_mov_b32_e32 v98, 0
	v_mov_b32_e32 v99, 0
	v_mov_b32_e32 v100, 0
	v_mov_b32_e32 v101, 0
	v_mov_b32_e32 v102, 0
	v_mov_b32_e32 v103, 0
	v_mov_b32_e32 v104, 0
	v_mov_b32_e32 v105, 0
	v_mov_b32_e32 v106, 0
	v_mov_b32_e32 v107, 0
	v_mov_b32_e32 v108, 0
	v_mov_b32_e32 v109, 0
	v_mov_b32_e32 v110, 0
	v_mov_b32_e32 v111, 0
	v_mov_b32_e32 v112, 0
	v_mov_b32_e32 v113, 0
	v_mov_b32_e32 v114, 0
	v_mov_b32_e32 v115, 0
	v_mov_b32_e32 v116, 0
	v_mov_b32_e32 v117, 0
	v_mov_b32_e32 v118, 0
	v_mov_b32_e32 v119, 0
	v_mov_b32_e32 v120, 0
	v_mov_b32_e32 v121, 0
	v_mov_b32_e32 v122, 0
	v_mov_b32_e32 v123, 0
	v_mov_b32_e32 v124, 0
	v_mov_b32_e32 v125, 0
	v_mov_b32_e32 v126, 0
	v_mov_b32_e32 v127, 0
	s_mov_b32 s63, 0
	s_waitcnt vmcnt(0)
	s_barrier
	s_add_u32 s56, s56, 0x80
	s_addc_u32 s57, s57, 0
	s_add_u32 m0, s62, 0x8800
	s_add_u32 s4, s56, 0x0
	s_addc_u32 s5, s57, 0
	global_load_lds_dwordx4 v162, s[4:5]
	s_add_u32 m0, s62, 0x9800
	s_add_u32 s4, s56, 0x72000
	s_addc_u32 s5, s57, 0
	global_load_lds_dwordx4 v162, s[4:5]
	s_add_u32 m0, s62, 0xa800
	s_add_u32 s4, s56, 0xe4000
	s_addc_u32 s5, s57, 0
	global_load_lds_dwordx4 v162, s[4:5]
	s_add_u32 m0, s62, 0xb800
	s_add_u32 s4, s56, 0x156000
	s_addc_u32 s5, s57, 0
	global_load_lds_dwordx4 v162, s[4:5]
	s_add_u32 m0, s62, 0xc800
	s_add_u32 s4, s56, 0x1c8000
	s_addc_u32 s5, s57, 0
	global_load_lds_dwordx4 v162, s[4:5]
	s_add_u32 m0, s62, 0xd800
	s_add_u32 s4, s56, 0x23a000
	s_addc_u32 s5, s57, 0
	global_load_lds_dwordx4 v162, s[4:5]
	s_add_u32 m0, s62, 0xe800
	s_add_u32 s4, s56, 0x2ac000
	s_addc_u32 s5, s57, 0
	global_load_lds_dwordx4 v162, s[4:5]
	s_add_u32 m0, s62, 0xf800
	s_add_u32 s4, s56, 0x31e000
	s_addc_u32 s5, s57, 0
	global_load_lds_dwordx4 v162, s[4:5]
	ds_read_b128 v[136:139], v156 offset:0
	ds_read_b128 v[140:143], v156 offset:2048
	ds_read_b128 v[144:147], v156 offset:4096
	ds_read_b128 v[148:151], v156 offset:6144
.Lg2_up_loop16:
	s_add_u32 s58, s58, 0x800
	s_addc_u32 s59, s59, 0
	global_load_dwordx4 v[200:203], v160, s[58:59] offset:0
	global_load_dwordx4 v[204:207], v160, s[58:59] offset:1024
	global_load_dwordx4 v[208:211], v161, s[58:59] offset:0
	global_load_dwordx4 v[240:243], v161, s[58:59] offset:1024
	ds_read_b128 v[164:167], v156 offset:8192
	ds_read_b128 v[168:171], v156 offset:10240
	ds_read_b128 v[172:175], v156 offset:12288
	ds_read_b128 v[176:179], v156 offset:14336
	s_waitcnt lgkmcnt(4)
	v_mfma_f32_16x16x32_bf16 v[0:3], v[184:187], v[136:139], v[0:3]
	v_mfma_f32_16x16x32_bf16 v[4:7], v[192:195], v[136:139], v[4:7]
	v_mfma_f32_16x16x32_bf16 v[8:11], v[184:187], v[140:143], v[8:11]
	v_mfma_f32_16x16x32_bf16 v[12:15], v[192:195], v[140:143], v[12:15]
	v_mfma_f32_16x16x32_bf16 v[16:19], v[184:187], v[144:147], v[16:19]
	v_mfma_f32_16x16x32_bf16 v[20:23], v[192:195], v[144:147], v[20:23]
	v_mfma_f32_16x16x32_bf16 v[24:27], v[184:187], v[148:151], v[24:27]
	v_mfma_f32_16x16x32_bf16 v[28:31], v[192:195], v[148:151], v[28:31]
	ds_read_b128 v[136:139], v156 offset:16384
	ds_read_b128 v[140:143], v156 offset:18432
	ds_read_b128 v[144:147], v156 offset:20480
	ds_read_b128 v[148:151], v156 offset:22528
	s_waitcnt lgkmcnt(4)
	v_mfma_f32_16x16x32_bf16 v[32:35], v[184:187], v[164:167], v[32:35]
	v_mfma_f32_16x16x32_bf16 v[36:39], v[192:195], v[164:167], v[36:39]
	v_mfma_f32_16x16x32_bf16 v[40:43], v[184:187], v[168:171], v[40:43]
	v_mfma_f32_16x16x32_bf16 v[44:47], v[192:195], v[168:171], v[44:47]
	v_mfma_f32_16x16x32_bf16 v[48:51], v[184:187], v[172:175], v[48:51]
	v_mfma_f32_16x16x32_bf16 v[52:55], v[192:195], v[172:175], v[52:55]
	v_mfma_f32_16x16x32_bf16 v[56:59], v[184:187], v[176:179], v[56:59]
	v_mfma_f32_16x16x32_bf16 v[60:63], v[192:195], v[176:179], v[60:63]
	ds_read_b128 v[164:167], v156 offset:24576
	ds_read_b128 v[168:171], v156 offset:26624
	ds_read_b128 v[172:175], v156 offset:28672
	ds_read_b128 v[176:179], v156 offset:30720
	s_waitcnt lgkmcnt(4)
	v_mfma_f32_16x16x32_bf16 v[64:67], v[184:187], v[136:139], v[64:67]
	v_mfma_f32_16x16x32_bf16 v[68:71], v[192:195], v[136:139], v[68:71]
	v_mfma_f32_16x16x32_bf16 v[72:75], v[184:187], v[140:143], v[72:75]
	v_mfma_f32_16x16x32_bf16 v[76:79], v[192:195], v[140:143], v[76:79]
	v_mfma_f32_16x16x32_bf16 v[80:83], v[184:187], v[144:147], v[80:83]
	v_mfma_f32_16x16x32_bf16 v[84:87], v[192:195], v[144:147], v[84:87]
	v_mfma_f32_16x16x32_bf16 v[88:91], v[184:187], v[148:151], v[88:91]
	v_mfma_f32_16x16x32_bf16 v[92:95], v[192:195], v[148:151], v[92:95]
	ds_read_b128 v[136:139], v157 offset:0
	ds_read_b128 v[140:143], v157 offset:2048
	ds_read_b128 v[144:147], v157 offset:4096
	ds_read_b128 v[148:151], v157 offset:6144
	s_waitcnt lgkmcnt(4)
	v_mfma_f32_16x16x32_bf16 v[96:99], v[184:187], v[164:167], v[96:99]
	v_mfma_f32_16x16x32_bf16 v[100:103], v[192:195], v[164:167], v[100:103]
	v_mfma_f32_16x16x32_bf16 v[104:107], v[184:187], v[168:171], v[104:107]
	v_mfma_f32_16x16x32_bf16 v[108:111], v[192:195], v[168:171], v[108:111]
	v_mfma_f32_16x16x32_bf16 v[112:115], v[184:187], v[172:175], v[112:115]
	v_mfma_f32_16x16x32_bf16 v[116:119], v[192:195], v[172:175], v[116:119]
	v_mfma_f32_16x16x32_bf16 v[120:123], v[184:187], v[176:179], v[120:123]
	v_mfma_f32_16x16x32_bf16 v[124:127], v[192:195], v[176:179], v[124:127]
	ds_read_b128 v[164:167], v157 offset:8192
	ds_read_b128 v[168:171], v157 offset:10240
	ds_read_b128 v[172:175], v157 offset:12288
	ds_read_b128 v[176:179], v157 offset:14336
	s_waitcnt lgkmcnt(4)
	v_mfma_f32_16x16x32_bf16 v[0:3], v[188:191], v[136:139], v[0:3]
	v_mfma_f32_16x16x32_bf16 v[4:7], v[196:199], v[136:139], v[4:7]
	v_mfma_f32_16x16x32_bf16 v[8:11], v[188:191], v[140:143], v[8:11]
	v_mfma_f32_16x16x32_bf16 v[12:15], v[196:199], v[140:143], v[12:15]
	v_mfma_f32_16x16x32_bf16 v[16:19], v[188:191], v[144:147], v[16:19]
	v_mfma_f32_16x16x32_bf16 v[20:23], v[196:199], v[144:147], v[20:23]
	v_mfma_f32_16x16x32_bf16 v[24:27], v[188:191], v[148:151], v[24:27]
	v_mfma_f32_16x16x32_bf16 v[28:31], v[196:199], v[148:151], v[28:31]
	ds_read_b128 v[136:139], v157 offset:16384
	ds_read_b128 v[140:143], v157 offset:18432
	ds_read_b128 v[144:147], v157 offset:20480
	ds_read_b128 v[148:151], v157 offset:22528
	s_waitcnt lgkmcnt(4)
	v_mfma_f32_16x16x32_bf16 v[32:35], v[188:191], v[164:167], v[32:35]
	v_mfma_f32_16x16x32_bf16 v[36:39], v[196:199], v[164:167], v[36:39]
	v_mfma_f32_16x16x32_bf16 v[40:43], v[188:191], v[168:171], v[40:43]
	v_mfma_f32_16x16x32_bf16 v[44:47], v[196:199], v[168:171], v[44:47]
	v_mfma_f32_16x16x32_bf16 v[48:51], v[188:191], v[172:175], v[48:51]
	v_mfma_f32_16x16x32_bf16 v[52:55], v[196:199], v[172:175], v[52:55]
	v_mfma_f32_16x16x32_bf16 v[56:59], v[188:191], v[176:179], v[56:59]
	v_mfma_f32_16x16x32_bf16 v[60:63], v[196:199], v[176:179], v[60:63]
	ds_read_b128 v[164:167], v157 offset:24576
	ds_read_b128 v[168:171], v157 offset:26624
	ds_read_b128 v[172:175], v157 offset:28672
	ds_read_b128 v[176:179], v157 offset:30720
	s_waitcnt lgkmcnt(4)
	v_mfma_f32_16x16x32_bf16 v[64:67], v[188:191], v[136:139], v[64:67]
	v_mfma_f32_16x16x32_bf16 v[68:71], v[196:199], v[136:139], v[68:71]
	v_mfma_f32_16x16x32_bf16 v[72:75], v[188:191], v[140:143], v[72:75]
	v_mfma_f32_16x16x32_bf16 v[76:79], v[196:199], v[140:143], v[76:79]
	v_mfma_f32_16x16x32_bf16 v[80:83], v[188:191], v[144:147], v[80:83]
	v_mfma_f32_16x16x32_bf16 v[84:87], v[196:199], v[144:147], v[84:87]
	v_mfma_f32_16x16x32_bf16 v[88:91], v[188:191], v[148:151], v[88:91]
	v_mfma_f32_16x16x32_bf16 v[92:95], v[196:199], v[148:151], v[92:95]
	s_waitcnt vmcnt(0) lgkmcnt(0)
	s_barrier
	s_cmp_ge_u32 s63, 2
	s_cbranch_scc1 .Lg2_up_nd16_0
	s_add_u32 s56, s56, 0x80
	s_addc_u32 s57, s57, 0
	s_add_u32 m0, s62, 0x0
	s_add_u32 s4, s56, 0x0
	s_addc_u32 s5, s57, 0
	global_load_lds_dwordx4 v162, s[4:5]
	s_add_u32 m0, s62, 0x1000
	s_add_u32 s4, s56, 0x72000
	s_addc_u32 s5, s57, 0
	global_load_lds_dwordx4 v162, s[4:5]
	s_add_u32 m0, s62, 0x2000
	s_add_u32 s4, s56, 0xe4000
	s_addc_u32 s5, s57, 0
	global_load_lds_dwordx4 v162, s[4:5]
	s_add_u32 m0, s62, 0x3000
	s_add_u32 s4, s56, 0x156000
	s_addc_u32 s5, s57, 0
	global_load_lds_dwordx4 v162, s[4:5]
	s_add_u32 m0, s62, 0x4000
	s_add_u32 s4, s56, 0x1c8000
	s_addc_u32 s5, s57, 0
	global_load_lds_dwordx4 v162, s[4:5]
	s_add_u32 m0, s62, 0x5000
	s_add_u32 s4, s56, 0x23a000
	s_addc_u32 s5, s57, 0
	global_load_lds_dwordx4 v162, s[4:5]
	s_add_u32 m0, s62, 0x6000
	s_add_u32 s4, s56, 0x2ac000
	s_addc_u32 s5, s57, 0
	global_load_lds_dwordx4 v162, s[4:5]
	s_add_u32 m0, s62, 0x7000
	s_add_u32 s4, s56, 0x31e000
	s_addc_u32 s5, s57, 0
	global_load_lds_dwordx4 v162, s[4:5]
.Lg2_up_nd16_0:
	ds_read_b128 v[136:139], v158 offset:0
	ds_read_b128 v[140:143], v158 offset:2048
	ds_read_b128 v[144:147], v158 offset:4096
	ds_read_b128 v[148:151], v158 offset:6144
	v_mfma_f32_16x16x32_bf16 v[96:99], v[188:191], v[164:167], v[96:99]
	v_mfma_f32_16x16x32_bf16 v[100:103], v[196:199], v[164:167], v[100:103]
	v_mfma_f32_16x16x32_bf16 v[104:107], v[188:191], v[168:171], v[104:107]
	v_mfma_f32_16x16x32_bf16 v[108:111], v[196:199], v[168:171], v[108:111]
	v_mfma_f32_16x16x32_bf16 v[112:115], v[188:191], v[172:175], v[112:115]
	v_mfma_f32_16x16x32_bf16 v[116:119], v[196:199], v[172:175], v[116:119]
	v_mfma_f32_16x16x32_bf16 v[120:123], v[188:191], v[176:179], v[120:123]
	v_mfma_f32_16x16x32_bf16 v[124:127], v[196:199], v[176:179], v[124:127]
	s_cmp_ge_u32 s63, 2
	s_cbranch_scc1 .Lg2_up_nb16_1
	s_add_u32 s58, s58, 0x800
	s_addc_u32 s59, s59, 0
	global_load_dwordx4 v[184:187], v160, s[58:59] offset:0
	global_load_dwordx4 v[188:191], v160, s[58:59] offset:1024
	global_load_dwordx4 v[192:195], v161, s[58:59] offset:0
	global_load_dwordx4 v[196:199], v161, s[58:59] offset:1024
.Lg2_up_nb16_1:
	ds_read_b128 v[164:167], v158 offset:8192
	ds_read_b128 v[168:171], v158 offset:10240
	ds_read_b128 v[172:175], v158 offset:12288
	ds_read_b128 v[176:179], v158 offset:14336
	s_waitcnt lgkmcnt(4)
	v_mfma_f32_16x16x32_bf16 v[0:3], v[200:203], v[136:139], v[0:3]
	v_mfma_f32_16x16x32_bf16 v[4:7], v[208:211], v[136:139], v[4:7]
	v_mfma_f32_16x16x32_bf16 v[8:11], v[200:203], v[140:143], v[8:11]
	v_mfma_f32_16x16x32_bf16 v[12:15], v[208:211], v[140:143], v[12:15]
	v_mfma_f32_16x16x32_bf16 v[16:19], v[200:203], v[144:147], v[16:19]
	v_mfma_f32_16x16x32_bf16 v[20:23], v[208:211], v[144:147], v[20:23]
	v_mfma_f32_16x16x32_bf16 v[24:27], v[200:203], v[148:151], v[24:27]
	v_mfma_f32_16x16x32_bf16 v[28:31], v[208:211], v[148:151], v[28:31]
	ds_read_b128 v[136:139], v158 offset:16384
	ds_read_b128 v[140:143], v158 offset:18432
	ds_read_b128 v[144:147], v158 offset:20480
	ds_read_b128 v[148:151], v158 offset:22528
	s_waitcnt lgkmcnt(4)
	v_mfma_f32_16x16x32_bf16 v[32:35], v[200:203], v[164:167], v[32:35]
	v_mfma_f32_16x16x32_bf16 v[36:39], v[208:211], v[164:167], v[36:39]
	v_mfma_f32_16x16x32_bf16 v[40:43], v[200:203], v[168:171], v[40:43]
	v_mfma_f32_16x16x32_bf16 v[44:47], v[208:211], v[168:171], v[44:47]
	v_mfma_f32_16x16x32_bf16 v[48:51], v[200:203], v[172:175], v[48:51]
	v_mfma_f32_16x16x32_bf16 v[52:55], v[208:211], v[172:175], v[52:55]
	v_mfma_f32_16x16x32_bf16 v[56:59], v[200:203], v[176:179], v[56:59]
	v_mfma_f32_16x16x32_bf16 v[60:63], v[208:211], v[176:179], v[60:63]
	ds_read_b128 v[164:167], v158 offset:24576
	ds_read_b128 v[168:171], v158 offset:26624
	ds_read_b128 v[172:175], v158 offset:28672
	ds_read_b128 v[176:179], v158 offset:30720
	s_waitcnt lgkmcnt(4)
	v_mfma_f32_16x16x32_bf16 v[64:67], v[200:203], v[136:139], v[64:67]
	v_mfma_f32_16x16x32_bf16 v[68:71], v[208:211], v[136:139], v[68:71]
	v_mfma_f32_16x16x32_bf16 v[72:75], v[200:203], v[140:143], v[72:75]
	v_mfma_f32_16x16x32_bf16 v[76:79], v[208:211], v[140:143], v[76:79]
	v_mfma_f32_16x16x32_bf16 v[80:83], v[200:203], v[144:147], v[80:83]
	v_mfma_f32_16x16x32_bf16 v[84:87], v[208:211], v[144:147], v[84:87]
	v_mfma_f32_16x16x32_bf16 v[88:91], v[200:203], v[148:151], v[88:91]
	v_mfma_f32_16x16x32_bf16 v[92:95], v[208:211], v[148:151], v[92:95]
	ds_read_b128 v[136:139], v159 offset:0
	ds_read_b128 v[140:143], v159 offset:2048
	ds_read_b128 v[144:147], v159 offset:4096
	ds_read_b128 v[148:151], v159 offset:6144
	s_waitcnt lgkmcnt(4)
	v_mfma_f32_16x16x32_bf16 v[96:99], v[200:203], v[164:167], v[96:99]
	v_mfma_f32_16x16x32_bf16 v[100:103], v[208:211], v[164:167], v[100:103]
	v_mfma_f32_16x16x32_bf16 v[104:107], v[200:203], v[168:171], v[104:107]
	v_mfma_f32_16x16x32_bf16 v[108:111], v[208:211], v[168:171], v[108:111]
	v_mfma_f32_16x16x32_bf16 v[112:115], v[200:203], v[172:175], v[112:115]
	v_mfma_f32_16x16x32_bf16 v[116:119], v[208:211], v[172:175], v[116:119]
	v_mfma_f32_16x16x32_bf16 v[120:123], v[200:203], v[176:179], v[120:123]
	v_mfma_f32_16x16x32_bf16 v[124:127], v[208:211], v[176:179], v[124:127]
	ds_read_b128 v[164:167], v159 offset:8192
	ds_read_b128 v[168:171], v159 offset:10240
	ds_read_b128 v[172:175], v159 offset:12288
	ds_read_b128 v[176:179], v159 offset:14336
	s_waitcnt lgkmcnt(4)
	v_mfma_f32_16x16x32_bf16 v[0:3], v[204:207], v[136:139], v[0:3]
	v_mfma_f32_16x16x32_bf16 v[4:7], v[240:243], v[136:139], v[4:7]
	v_mfma_f32_16x16x32_bf16 v[8:11], v[204:207], v[140:143], v[8:11]
	v_mfma_f32_16x16x32_bf16 v[12:15], v[240:243], v[140:143], v[12:15]
	v_mfma_f32_16x16x32_bf16 v[16:19], v[204:207], v[144:147], v[16:19]
	v_mfma_f32_16x16x32_bf16 v[20:23], v[240:243], v[144:147], v[20:23]
	v_mfma_f32_16x16x32_bf16 v[24:27], v[204:207], v[148:151], v[24:27]
	v_mfma_f32_16x16x32_bf16 v[28:31], v[240:243], v[148:151], v[28:31]
	ds_read_b128 v[136:139], v159 offset:16384
	ds_read_b128 v[140:143], v159 offset:18432
	ds_read_b128 v[144:147], v159 offset:20480
	ds_read_b128 v[148:151], v159 offset:22528
	s_waitcnt lgkmcnt(4)
	v_mfma_f32_16x16x32_bf16 v[32:35], v[204:207], v[164:167], v[32:35]
	v_mfma_f32_16x16x32_bf16 v[36:39], v[240:243], v[164:167], v[36:39]
	v_mfma_f32_16x16x32_bf16 v[40:43], v[204:207], v[168:171], v[40:43]
	v_mfma_f32_16x16x32_bf16 v[44:47], v[240:243], v[168:171], v[44:47]
	v_mfma_f32_16x16x32_bf16 v[48:51], v[204:207], v[172:175], v[48:51]
	v_mfma_f32_16x16x32_bf16 v[52:55], v[240:243], v[172:175], v[52:55]
	v_mfma_f32_16x16x32_bf16 v[56:59], v[204:207], v[176:179], v[56:59]
	v_mfma_f32_16x16x32_bf16 v[60:63], v[240:243], v[176:179], v[60:63]
	ds_read_b128 v[164:167], v159 offset:24576
	ds_read_b128 v[168:171], v159 offset:26624
	ds_read_b128 v[172:175], v159 offset:28672
	ds_read_b128 v[176:179], v159 offset:30720
	s_waitcnt lgkmcnt(4)
	v_mfma_f32_16x16x32_bf16 v[64:67], v[204:207], v[136:139], v[64:67]
	v_mfma_f32_16x16x32_bf16 v[68:71], v[240:243], v[136:139], v[68:71]
	v_mfma_f32_16x16x32_bf16 v[72:75], v[204:207], v[140:143], v[72:75]
	v_mfma_f32_16x16x32_bf16 v[76:79], v[240:243], v[140:143], v[76:79]
	v_mfma_f32_16x16x32_bf16 v[80:83], v[204:207], v[144:147], v[80:83]
	v_mfma_f32_16x16x32_bf16 v[84:87], v[240:243], v[144:147], v[84:87]
	v_mfma_f32_16x16x32_bf16 v[88:91], v[204:207], v[148:151], v[88:91]
	v_mfma_f32_16x16x32_bf16 v[92:95], v[240:243], v[148:151], v[92:95]
	s_waitcnt vmcnt(0) lgkmcnt(0)
	s_barrier
	s_cmp_ge_u32 s63, 2
	s_cbranch_scc1 .Lg2_up_nd16_1
	s_add_u32 s56, s56, 0x80
	s_addc_u32 s57, s57, 0
	s_add_u32 m0, s62, 0x8800
	s_add_u32 s4, s56, 0x0
	s_addc_u32 s5, s57, 0
	global_load_lds_dwordx4 v162, s[4:5]
	s_add_u32 m0, s62, 0x9800
	s_add_u32 s4, s56, 0x72000
	s_addc_u32 s5, s57, 0
	global_load_lds_dwordx4 v162, s[4:5]
	s_add_u32 m0, s62, 0xa800
	s_add_u32 s4, s56, 0xe4000
	s_addc_u32 s5, s57, 0
	global_load_lds_dwordx4 v162, s[4:5]
	s_add_u32 m0, s62, 0xb800
	s_add_u32 s4, s56, 0x156000
	s_addc_u32 s5, s57, 0
	global_load_lds_dwordx4 v162, s[4:5]
	s_add_u32 m0, s62, 0xc800
	s_add_u32 s4, s56, 0x1c8000
	s_addc_u32 s5, s57, 0
	global_load_lds_dwordx4 v162, s[4:5]
	s_add_u32 m0, s62, 0xd800
	s_add_u32 s4, s56, 0x23a000
	s_addc_u32 s5, s57, 0
	global_load_lds_dwordx4 v162, s[4:5]
	s_add_u32 m0, s62, 0xe800
	s_add_u32 s4, s56, 0x2ac000
	s_addc_u32 s5, s57, 0
	global_load_lds_dwordx4 v162, s[4:5]
	s_add_u32 m0, s62, 0xf800
	s_add_u32 s4, s56, 0x31e000
	s_addc_u32 s5, s57, 0
	global_load_lds_dwordx4 v162, s[4:5]
	ds_read_b128 v[136:139], v156 offset:0
	ds_read_b128 v[140:143], v156 offset:2048
	ds_read_b128 v[144:147], v156 offset:4096
	ds_read_b128 v[148:151], v156 offset:6144
.Lg2_up_nd16_1:
	v_mfma_f32_16x16x32_bf16 v[96:99], v[204:207], v[164:167], v[96:99]
	v_mfma_f32_16x16x32_bf16 v[100:103], v[240:243], v[164:167], v[100:103]
	v_mfma_f32_16x16x32_bf16 v[104:107], v[204:207], v[168:171], v[104:107]
	v_mfma_f32_16x16x32_bf16 v[108:111], v[240:243], v[168:171], v[108:111]
	v_mfma_f32_16x16x32_bf16 v[112:115], v[204:207], v[172:175], v[112:115]
	v_mfma_f32_16x16x32_bf16 v[116:119], v[240:243], v[172:175], v[116:119]
	v_mfma_f32_16x16x32_bf16 v[120:123], v[204:207], v[176:179], v[120:123]
	v_mfma_f32_16x16x32_bf16 v[124:127], v[240:243], v[176:179], v[124:127]
	s_add_i32 s63, s63, 2
	s_cmp_lt_u32 s63, 4
	s_cbranch_scc1 .Lg2_up_loop16
	s_branch .Lg2_up_episel
